# v16 + attention window mask: one-sided compare+select per score (2 ops instead of 5), compares run ahead through 6 rotating lane masks
# speedup vs baseline: 1.0035x; 1.0009x over previous
; #define LAS __attribute__((address_space(3)))
; __device__ __forceinline__ s16x4 vtr(LAS const unsigned char* p) { return __builtin_bit_cast(s16x4, __builtin_amdgcn_ds_read_tr16_b64_v4i16((LAS v4i16_t*)p)); }
; __device__ __forceinline__ void att_block(const bf16x8 (&kf)[4], const bf16x8 (&qf)[4], const bf16x8 (&va)[4], f32x16& o0, f32x16& o1, float& mrun, float& lrun, bool domask, int lo_, int hi_) {
;     f32x16 st;
; #pragma unroll
;     for (int i = 0; i < 16; ++i) st[i] = 0.f;
; #pragma unroll
;     for (int kk = 0; kk < 4; ++kk) st = __builtin_amdgcn_mfma_f32_32x32x16_bf16(kf[kk], qf[kk], st, 0, 0, 0);
;     if (domask) {
;         asm volatile("" : "+v"(lo_), "+v"(hi_));
; #pragma unroll
;         for (int i = 0; i < 16; ++i) { const int ci = (i & 3) + 8 * (i >> 2); st[i] = ((ci - lo_) | (hi_ - ci)) < 0 ? -INFINITY : st[i]; }
;     }
;     float bmax = -INFINITY;
; #pragma unroll
;     for (int i = 0; i < 16; ++i) bmax = fmaxf(bmax, st[i]);
;     bmax = fmaxf(bmax, __shfl_xor(bmax, 32));
; __device__ __forceinline__ void att_phase(unsigned char* ws, LAS unsigned char* lds, int lane, int wave, int G) {
;     ...
;         for (int kb = 0; kb < 6; ++kb) {
;             asm volatile("s_waitcnt vmcnt(0)" ::: "memory");
;             if (kb < 5) ATT_DMA_KV(P, kb + 1, sb ^ 1);
;             else if (hn) ATT_DMA_KV(N, 0, sb ^ 1);
;             bf16x8 kf[4], va[4];
; #pragma unroll
;             for (int kk = 0; kk < 4; ++kk) kf[kk] = *(LAS const bf16x8*)(kfb + sb * 4096 + (((2 * kk + h) ^ (qc & 7)) << 4));
;             LAS const unsigned char* trs = trb + 8192 + sb * 4096;
; #pragma unroll
;             for (int s = 0; s < 2; ++s) {
;                 const s16x4 lo0 = vtr(trs + (16 * s) * VP), hi0 = vtr(trs + (16 * s + 8) * VP);
;                 const s16x4 lo1 = vtr(trs + (16 * s) * VP + 64), hi1 = vtr(trs + (16 * s + 8) * VP + 64);
;                 va[2 * s] = (bf16x8){lo0[0], lo0[1], lo0[2], lo0[3], hi0[0], hi0[1], hi0[2], hi0[3]};
;                 va[2 * s + 1] = (bf16x8){lo1[0], lo1[1], lo1[2], lo1[3], hi1[0], hi1[1], hi1[2], hi1[3]};
;             }
;             if (kb <= 4) {
;                 att_block(kf, qfA, va, oA0, oA1, mA, lA, kb == 0 || kb == 4 || kminA > 32 * kb, mloA - 4 * h - 32 * kb, qc + 128 - 4 * h - 32 * kb);
.LBB0_80:
	v_add_u32_e32 v0, 0xffffffa0, v191
	v_mul_lo_u32 v0, s56, v0
	v_add_u32_e32 v4, s11, v0
	v_max_i32_e32 v164, 0, v4
	v_lshl_add_u64 v[0:1], s[12:13], 0, v[164:165]
	v_lshlrev_b64 v[0:1], 7, v[0:1]
	s_add_i32 s57, s33, 0x1000
	s_lshl_b32 s6, s56, 3
	s_waitcnt vmcnt(0)
	v_lshl_add_u64 v[2:3], v[180:181], 0, v[0:1]
	s_mov_b32 m0, s57
	s_add_i32 s7, s33, 0x3000
	v_add_u32_e32 v4, s6, v4
	global_load_lds_dwordx4 v[2:3], off
	v_lshl_add_u64 v[0:1], v[182:183], 0, v[0:1]
	s_mov_b32 m0, s7
	v_max_i32_e32 v164, 0, v4
	global_load_lds_dwordx4 v[0:1], off
	v_lshl_add_u64 v[0:1], s[12:13], 0, v[164:165]
	v_lshlrev_b64 v[0:1], 7, v[0:1]
	v_readlane_b32 s15, v254, 28
	v_lshl_add_u64 v[2:3], v[180:181], 0, v[0:1]
	s_mov_b32 m0, s15
	v_readlane_b32 s15, v254, 29
	v_add_u32_e32 v4, s6, v4
	global_load_lds_dwordx4 v[2:3], off
	v_lshl_add_u64 v[0:1], v[182:183], 0, v[0:1]
	s_mov_b32 m0, s15
	v_max_i32_e32 v164, 0, v4
	global_load_lds_dwordx4 v[0:1], off
	v_lshl_add_u64 v[0:1], s[12:13], 0, v[164:165]
	v_lshlrev_b64 v[0:1], 7, v[0:1]
	s_add_i32 s15, s33, 0x1800
	v_lshl_add_u64 v[2:3], v[180:181], 0, v[0:1]
	s_mov_b32 m0, s15
	s_add_i32 s17, s33, 0x3800
	v_add_u32_e32 v51, s6, v4
	global_load_lds_dwordx4 v[2:3], off
	v_lshl_add_u64 v[0:1], v[182:183], 0, v[0:1]
	s_mov_b32 m0, s17
	v_max_i32_e32 v164, 0, v51
	global_load_lds_dwordx4 v[0:1], off
	v_lshl_add_u64 v[0:1], s[12:13], 0, v[164:165]
	v_lshlrev_b64 v[0:1], 7, v[0:1]
	s_add_i32 s21, s33, 0x1c00
	v_lshl_add_u64 v[2:3], v[180:181], 0, v[0:1]
	s_mov_b32 m0, s21
	v_readlane_b32 s59, v254, 30
	global_load_lds_dwordx4 v[2:3], off
	v_lshl_add_u64 v[0:1], v[182:183], 0, v[0:1]
	s_mov_b32 m0, s59
	v_max_i32_e32 v199, s58, v189
	global_load_lds_dwordx4 v[0:1], off
	ds_read_b128 v[0:3], v225
	ds_read_b128 v[16:19], v226
	s_waitcnt vmcnt(0) lgkmcnt(0)
	v_mfma_f32_32x32x16_bf16 v[0:15], v[0:3], v[128:131], 0
	ds_read_b128 v[20:23], v228
	s_mov_b32 s59, 0xff800000
	v_mfma_f32_32x32x16_bf16 v[0:15], v[16:19], v[124:127], v[0:15]
	ds_read_b128 v[16:19], v227
	ds_read_b64_tr_b16 v[34:35], v229 offset:8192
	ds_read_b64_tr_b16 v[36:37], v229 offset:9216
	ds_read_b64_tr_b16 v[40:41], v229 offset:9280
	ds_read_b64_tr_b16 v[38:39], v229 offset:8256
	ds_read_b64_tr_b16 v[42:43], v229 offset:10240
	ds_read_b64_tr_b16 v[44:45], v229 offset:11264
	ds_read_b64_tr_b16 v[48:49], v229 offset:11328
	ds_read_b64_tr_b16 v[46:47], v229 offset:10304
	s_waitcnt lgkmcnt(8)
	v_mfma_f32_32x32x16_bf16 v[0:15], v[16:19], v[120:123], v[0:15]
	v_sub_u32_e32 v16, v199, v193
	v_mov_b32_e32 v17, v214
	s_waitcnt lgkmcnt(0)
	s_nop 0
	v_mfma_f32_32x32x16_bf16 v[0:15], v[20:23], v[116:119], v[0:15]
	s_nop 6
	v_cmp_ge_i32_e32 vcc, 0, v16
	v_cmp_ge_i32_e64 s[24:25], 1, v16
	v_cmp_ge_i32_e64 s[26:27], 2, v16
	v_cmp_ge_i32_e64 s[28:29], 3, v16
	v_cmp_ge_i32_e64 s[30:31], 8, v16
	v_cmp_ge_i32_e64 s[34:35], 9, v16
	v_cndmask_b32_e32 v0, v211, v0, vcc
	v_cmp_ge_i32_e32 vcc, 10, v16
	v_cndmask_b32_e64 v1, v211, v1, s[24:25]
	v_cmp_ge_i32_e64 s[24:25], 11, v16
	v_cndmask_b32_e64 v2, v211, v2, s[26:27]
	v_cmp_ge_i32_e64 s[26:27], 16, v16
	v_cndmask_b32_e64 v3, v211, v3, s[28:29]
	v_cmp_ge_i32_e64 s[28:29], 17, v16
	v_cndmask_b32_e64 v4, v211, v4, s[30:31]
	v_cmp_ge_i32_e64 s[30:31], 18, v16
	v_cndmask_b32_e64 v5, v211, v5, s[34:35]
	v_cmp_ge_i32_e64 s[34:35], 19, v16
	v_cndmask_b32_e32 v6, v211, v6, vcc
	v_cmp_ge_i32_e32 vcc, 24, v16
	v_cndmask_b32_e64 v7, v211, v7, s[24:25]
	v_cmp_ge_i32_e64 s[24:25], 25, v16
	v_cndmask_b32_e64 v8, v211, v8, s[26:27]
	v_cmp_ge_i32_e64 s[26:27], 26, v16
	v_cndmask_b32_e64 v9, v211, v9, s[28:29]
	v_cmp_ge_i32_e64 s[28:29], 27, v16
	v_cndmask_b32_e64 v10, v211, v10, s[30:31]
	v_cndmask_b32_e64 v11, v211, v11, s[34:35]
	v_cndmask_b32_e32 v56, v211, v12, vcc
	v_cndmask_b32_e64 v57, v211, v13, s[24:25]
	v_cndmask_b32_e64 v58, v211, v14, s[26:27]
	v_cndmask_b32_e64 v59, v211, v15, s[28:29]
	s_nop 0
	s_nop 0
	v_max3_f32 v12, v0, s59, v1
	v_max3_f32 v12, v12, v2, v3
	v_max3_f32 v12, v12, v4, v5
	v_max3_f32 v12, v12, v6, v7
	v_max3_f32 v12, v12, v8, v9
	v_xor_b32_e32 v13, 32, v206
	v_max3_f32 v12, v12, v10, v11
	v_cmp_lt_i32_e32 vcc, v13, v208
	v_max3_f32 v12, v12, v56, v57
	v_max3_f32 v12, v12, v58, v59
	v_cndmask_b32_e32 v13, v206, v13, vcc
	v_lshlrev_b32_e32 v201, 2, v13
	ds_bpermute_b32 v13, v201, v12
	s_mov_b32 s59, 0xf149f2ca
	s_waitcnt lgkmcnt(0)
; #define LAS __attribute__((address_space(3)))
; __device__ __forceinline__ void att_block(const bf16x8 (&kf)[4], const bf16x8 (&qf)[4], const bf16x8 (&va)[4], f32x16& o0, f32x16& o1, float& mrun, float& lrun, bool domask, int lo_, int hi_) {
;     ...
;     const float mnew = fmaxf(mrun, bmax);
;     float lsum = 0.f;
; #pragma unroll
;     for (int i = 0; i < 16; ++i) { st[i] = __builtin_amdgcn_exp2f(st[i] - mnew); lsum += st[i]; }
;     lsum += __shfl_xor(lsum, 32);
;     const float alpha = __builtin_amdgcn_exp2f(mrun - mnew);
;     lrun = lrun * alpha + lsum; mrun = mnew;
; #pragma unroll
;     for (int i = 0; i < 16; ++i) { o0[i] *= alpha; o1[i] *= alpha; }
; #pragma unroll
;     for (int s = 0; s < 2; ++s) { v4u w; w.x = pk2(st[8 * s], st[8 * s + 1]); w.y = pk2(st[8 * s + 2], st[8 * s + 3]); w.z = pk2(st[8 * s + 4], st[8 * s + 5]); w.w = pk2(st[8 * s + 6], st[8 * s + 7]);
;         const bf16x8 pb = __builtin_bit_cast(bf16x8, w);
;         o0 = __builtin_amdgcn_mfma_f32_32x32x16_bf16(va[2 * s], pb, o0, 0, 0, 0);
;         o1 = __builtin_amdgcn_mfma_f32_32x32x16_bf16(va[2 * s + 1], pb, o1, 0, 0, 0); }
; __device__ __forceinline__ void att_phase(unsigned char* ws, LAS unsigned char* lds, int lane, int wave, int G) {
;     ...
;         for (int kb = 0; kb < 6; ++kb) {
;             asm volatile("s_waitcnt vmcnt(0)" ::: "memory");
;             if (kb < 5) ATT_DMA_KV(P, kb + 1, sb ^ 1);
;             else if (hn) ATT_DMA_KV(N, 0, sb ^ 1);
;             bf16x8 kf[4], va[4];
; #pragma unroll
;             for (int kk = 0; kk < 4; ++kk) kf[kk] = *(LAS const bf16x8*)(kfb + sb * 4096 + (((2 * kk + h) ^ (qc & 7)) << 4));
;             LAS const unsigned char* trs = trb + 8192 + sb * 4096;
; #pragma unroll
;             for (int s = 0; s < 2; ++s) {
;                 const s16x4 lo0 = vtr(trs + (16 * s) * VP), hi0 = vtr(trs + (16 * s + 8) * VP);
;                 const s16x4 lo1 = vtr(trs + (16 * s) * VP + 64), hi1 = vtr(trs + (16 * s + 8) * VP + 64);
;                 va[2 * s] = (bf16x8){lo0[0], lo0[1], lo0[2], lo0[3], hi0[0], hi0[1], hi0[2], hi0[3]};
;                 va[2 * s + 1] = (bf16x8){lo1[0], lo1[1], lo1[2], lo1[3], hi1[0], hi1[1], hi1[2], hi1[3]};
;             }
;             if (kb <= 4) {
;                 att_block(kf, qfA, va, oA0, oA1, mA, lA, kb == 0 || kb == 4 || kminA > 32 * kb, mloA - 4 * h - 32 * kb, qc + 128 - 4 * h - 32 * kb);
	v_max3_f32 v50, v12, v13, s59
	v_sub_f32_e32 v0, v0, v50
	v_exp_f32_e32 v16, v0
	v_sub_f32_e32 v0, v1, v50
	v_exp_f32_e32 v17, v0
	v_sub_f32_e32 v1, v2, v50
	v_exp_f32_e32 v18, v1
	v_sub_f32_e32 v1, v3, v50
	v_exp_f32_e32 v19, v1
	v_sub_f32_e32 v1, v4, v50
	v_add_f32_e32 v0, 0, v16
	v_exp_f32_e32 v20, v1
	v_sub_f32_e32 v1, v5, v50
	v_add_f32_e32 v0, v17, v0
	v_exp_f32_e32 v21, v1
	v_sub_f32_e32 v1, v6, v50
	v_add_f32_e32 v0, v18, v0
	v_exp_f32_e32 v22, v1
	v_sub_f32_e32 v1, v7, v50
	v_add_f32_e32 v0, v19, v0
	v_exp_f32_e32 v23, v1
	v_sub_f32_e32 v1, v8, v50
	v_add_f32_e32 v0, v20, v0
	v_exp_f32_e32 v60, v1
	v_sub_f32_e32 v1, v9, v50
	v_add_f32_e32 v0, v21, v0
	v_exp_f32_e32 v61, v1
	v_add_f32_e32 v0, v22, v0
	v_add_f32_e32 v0, v23, v0
	v_add_f32_e32 v0, v60, v0
	v_add_f32_e32 v62, v61, v0
	v_sub_f32_e32 v0, 0xf149f2ca, v50
	v_exp_f32_e32 v0, v0
	v_sub_f32_e32 v1, v10, v50
	v_cvt_pk_bf16_f32 v52, v16, v17
	v_sub_f32_e32 v16, v56, v50
	v_mul_f32_e32 v0, 0, v0
	v_exp_f32_e32 v63, v1
	v_sub_f32_e32 v64, v11, v50
	v_mov_b32_e32 v1, v0
	v_mov_b32_e32 v2, v0
	v_mov_b32_e32 v3, v0
	v_mov_b32_e32 v4, v0
	v_mov_b32_e32 v5, v0
	v_mov_b32_e32 v6, v0
	v_mov_b32_e32 v7, v0
	v_mov_b32_e32 v8, v0
	v_mov_b32_e32 v9, v0
	v_mov_b32_e32 v10, v0
	v_mov_b32_e32 v11, v0
	v_mov_b32_e32 v12, v0
	v_mov_b32_e32 v13, v0
	v_mov_b32_e32 v14, v0
	v_mov_b32_e32 v15, v0
	v_cvt_pk_bf16_f32 v53, v18, v19
	v_cvt_pk_bf16_f32 v54, v20, v21
	v_cvt_pk_bf16_f32 v55, v22, v23
	v_exp_f32_e32 v56, v16
	v_sub_f32_e32 v16, v57, v50
	v_mfma_f32_32x32x16_bf16 v[18:33], v[34:37], v[52:55], v[0:15]
	v_exp_f32_e32 v57, v16
	v_mov_b64_e32 v[16:17], v[14:15]
	v_sub_f32_e32 v34, v58, v50
	v_exp_f32_e32 v64, v64
	v_cvt_pk_bf16_f32 v36, v56, v57
	s_nop 1
	v_mov_b64_e32 v[14:15], v[12:13]
	v_mov_b64_e32 v[12:13], v[10:11]
	v_mov_b64_e32 v[10:11], v[8:9]
	v_mov_b64_e32 v[8:9], v[6:7]
	v_mov_b64_e32 v[6:7], v[4:5]
	v_mov_b64_e32 v[4:5], v[2:3]
	v_mov_b64_e32 v[2:3], v[0:1]
	v_exp_f32_e32 v1, v34
	v_sub_f32_e32 v34, v59, v50
	v_mfma_f32_32x32x16_bf16 v[2:17], v[38:41], v[52:55], v[2:17]
	v_exp_f32_e32 v38, v34
	v_add_f32_e32 v39, v63, v62
	v_add_f32_e32 v39, v64, v39
	v_cvt_pk_bf16_f32 v34, v60, v61
	v_cvt_pk_bf16_f32 v35, v63, v64
	v_cvt_pk_bf16_f32 v37, v1, v38
	v_add_f32_e32 v39, v56, v39
	v_add_f32_e32 v39, v57, v39
	v_mfma_f32_32x32x16_bf16 v[18:33], v[42:45], v[34:37], v[18:33]
	v_add_f32_e32 v1, v1, v39
	v_add_f32_e32 v1, v38, v1
	ds_bpermute_b32 v232, v201, v1
	v_mfma_f32_32x32x16_bf16 v[2:17], v[46:49], v[34:37], v[2:17]
	v_add_u32_e32 v38, s6, v51
	v_max_i32_e32 v164, 0, v38
	v_lshl_add_u64 v[34:35], s[12:13], 0, v[164:165]
	v_lshlrev_b64 v[34:35], 7, v[34:35]
	s_mov_b32 m0, s33
	s_waitcnt vmcnt(0)
	v_lshl_add_u64 v[36:37], v[180:181], 0, v[34:35]
	v_add_u32_e32 v38, s6, v38
	global_load_lds_dwordx4 v[36:37], off
	v_lshl_add_u64 v[34:35], v[182:183], 0, v[34:35]
	s_mov_b32 m0, s44
	v_max_i32_e32 v164, 0, v38
	global_load_lds_dwordx4 v[34:35], off
	v_lshl_add_u64 v[34:35], s[12:13], 0, v[164:165]
	v_lshlrev_b64 v[34:35], 7, v[34:35]
	v_lshl_add_u64 v[36:37], v[180:181], 0, v[34:35]
	s_mov_b32 m0, s66
	v_add_u32_e32 v38, s6, v38
	global_load_lds_dwordx4 v[36:37], off
	v_lshl_add_u64 v[34:35], v[182:183], 0, v[34:35]
	s_mov_b32 m0, s67
	v_max_i32_e32 v164, 0, v38
	global_load_lds_dwordx4 v[34:35], off
	v_lshl_add_u64 v[34:35], s[12:13], 0, v[164:165]
	v_lshlrev_b64 v[34:35], 7, v[34:35]
	v_lshl_add_u64 v[36:37], v[180:181], 0, v[34:35]
	s_mov_b32 m0, s48
	v_lshl_add_u64 v[34:35], v[182:183], 0, v[34:35]
	global_load_lds_dwordx4 v[36:37], off
	s_mov_b32 m0, s49
	v_readlane_b32 s59, v254, 27
	global_load_lds_dwordx4 v[34:35], off
	v_add_u32_e32 v34, s6, v38
	v_max_i32_e32 v164, 0, v34
	v_lshl_add_u64 v[34:35], s[12:13], 0, v[164:165]
	v_lshlrev_b64 v[34:35], 7, v[34:35]
	v_lshl_add_u64 v[36:37], v[180:181], 0, v[34:35]
	s_mov_b32 m0, s72
	v_lshl_add_u64 v[34:35], v[182:183], 0, v[34:35]
	global_load_lds_dwordx4 v[36:37], off
	s_mov_b32 m0, s59
	s_cmp_gt_i32 s58, 32
	global_load_lds_dwordx4 v[34:35], off
	ds_read_b128 v[68:71], v225 offset:4096
	ds_read_b128 v[64:67], v226 offset:4096
	s_waitcnt lgkmcnt(0)
	v_mfma_f32_32x32x16_bf16 v[34:49], v[68:71], v[128:131], 0
	ds_read_b128 v[60:63], v227 offset:4096
	ds_read_b128 v[56:59], v228 offset:4096
	s_waitcnt vmcnt(0)
	ds_read_b64_tr_b16 v[52:53], v229 offset:12288
	ds_read_b64_tr_b16 v[54:55], v229 offset:13312
	ds_read_b64_tr_b16 v[94:95], v229 offset:13376
	ds_read_b64_tr_b16 v[92:93], v229 offset:12352
	ds_read_b64_tr_b16 v[88:89], v229 offset:14336
	ds_read_b64_tr_b16 v[90:91], v229 offset:15360
	ds_read_b64_tr_b16 v[86:87], v229 offset:15424
	ds_read_b64_tr_b16 v[84:85], v229 offset:14400
	v_mfma_f32_32x32x16_bf16 v[34:49], v[64:67], v[124:127], v[34:49]
	s_waitcnt lgkmcnt(9)
	v_mfma_f32_32x32x16_bf16 v[34:49], v[60:63], v[120:123], v[34:49]
	s_waitcnt lgkmcnt(8)
	v_mfma_f32_32x32x16_bf16 v[34:49], v[56:59], v[116:119], v[34:49]
	s_cbranch_scc0 .LBB0_82
	v_sub_u32_e32 v51, v199, v215
	v_mov_b32_e32 v72, v216
	s_nop 0
	s_nop 1
	v_cmp_ge_i32_e32 vcc, 0, v51
	v_cmp_ge_i32_e64 s[24:25], 1, v51
	v_cmp_ge_i32_e64 s[26:27], 2, v51
	v_cmp_ge_i32_e64 s[28:29], 3, v51
	v_cmp_ge_i32_e64 s[30:31], 8, v51
	v_cmp_ge_i32_e64 s[34:35], 9, v51
	v_cndmask_b32_e32 v34, v211, v34, vcc
	v_cmp_ge_i32_e32 vcc, 10, v51
	v_cndmask_b32_e64 v35, v211, v35, s[24:25]
	v_cmp_ge_i32_e64 s[24:25], 11, v51
	v_cndmask_b32_e64 v36, v211, v36, s[26:27]
	v_cmp_ge_i32_e64 s[26:27], 16, v51
	v_cndmask_b32_e64 v37, v211, v37, s[28:29]
	v_cmp_ge_i32_e64 s[28:29], 17, v51
	v_cndmask_b32_e64 v38, v211, v38, s[30:31]
	v_cmp_ge_i32_e64 s[30:31], 18, v51
	v_cndmask_b32_e64 v39, v211, v39, s[34:35]
	v_cmp_ge_i32_e64 s[34:35], 19, v51
	v_cndmask_b32_e32 v40, v211, v40, vcc
	v_cmp_ge_i32_e32 vcc, 24, v51
	v_cndmask_b32_e64 v41, v211, v41, s[24:25]
	v_cmp_ge_i32_e64 s[24:25], 25, v51
	v_cndmask_b32_e64 v42, v211, v42, s[26:27]
	v_cmp_ge_i32_e64 s[26:27], 26, v51
	v_cndmask_b32_e64 v43, v211, v43, s[28:29]
	v_cmp_ge_i32_e64 s[28:29], 27, v51
	v_cndmask_b32_e64 v44, v211, v44, s[30:31]
	v_cndmask_b32_e64 v45, v211, v45, s[34:35]
	v_cndmask_b32_e32 v46, v211, v46, vcc
	v_cndmask_b32_e64 v47, v211, v47, s[24:25]
	v_cndmask_b32_e64 v48, v211, v48, s[26:27]
	v_cndmask_b32_e64 v49, v211, v49, s[28:29]
	s_nop 0
	s_nop 1
; __device__ __forceinline__ unsigned pk2(float lo, float hi) { return pg8::cvt_pk_bf16(lo, hi); }
; __device__ __forceinline__ void att_block(const bf16x8 (&kf)[4], const bf16x8 (&qf)[4], const bf16x8 (&va)[4], f32x16& o0, f32x16& o1, float& mrun, float& lrun, bool domask, int lo_, int hi_) {
;     ...
;         for (int i = 0; i < 16; ++i) { const int ci = (i & 3) + 8 * (i >> 2); st[i] = ((ci - lo_) | (hi_ - ci)) < 0 ? -INFINITY : st[i]; }
;     }
;     float bmax = -INFINITY;
; #pragma unroll
;     for (int i = 0; i < 16; ++i) bmax = fmaxf(bmax, st[i]);
;     bmax = fmaxf(bmax, __shfl_xor(bmax, 32));
;     const float mnew = fmaxf(mrun, bmax);
;     float lsum = 0.f;
; #pragma unroll
;     for (int i = 0; i < 16; ++i) { st[i] = __builtin_amdgcn_exp2f(st[i] - mnew); lsum += st[i]; }
;     lsum += __shfl_xor(lsum, 32);
;     const float alpha = __builtin_amdgcn_exp2f(mrun - mnew);
;     lrun = lrun * alpha + lsum; mrun = mnew;
; #pragma unroll
;     for (int i = 0; i < 16; ++i) { o0[i] *= alpha; o1[i] *= alpha; }
; #pragma unroll
;     for (int s = 0; s < 2; ++s) { v4u w; w.x = pk2(st[8 * s], st[8 * s + 1]); w.y = pk2(st[8 * s + 2], st[8 * s + 3]); w.z = pk2(st[8 * s + 4], st[8 * s + 5]); w.w = pk2(st[8 * s + 6], st[8 * s + 7]);
;         const bf16x8 pb = __builtin_bit_cast(bf16x8, w);
;         o0 = __builtin_amdgcn_mfma_f32_32x32x16_bf16(va[2 * s], pb, o0, 0, 0, 0);
;         o1 = __builtin_amdgcn_mfma_f32_32x32x16_bf16(va[2 * s + 1], pb, o1, 0, 0, 0); }
.LBB0_82:
	s_mov_b32 s59, 0xff800000
	s_nop 9
	v_max3_f32 v51, v34, s59, v35
	v_max3_f32 v51, v51, v36, v37
	v_max3_f32 v51, v51, v38, v39
	v_max3_f32 v51, v51, v40, v41
	v_max3_f32 v51, v51, v42, v43
	v_max3_f32 v51, v51, v44, v45
	v_max3_f32 v51, v51, v46, v47
	v_max3_f32 v51, v51, v48, v49
	ds_bpermute_b32 v72, v201, v51
	v_max_i32_e32 v237, s14, v189
	s_mov_b32 s60, 0xff800000
	s_waitcnt lgkmcnt(0)
	v_max3_f32 v148, v50, v51, v72
	v_sub_f32_e32 v34, v34, v148
	v_exp_f32_e32 v72, v34
	v_sub_f32_e32 v35, v35, v148
	v_exp_f32_e32 v73, v35
	v_sub_f32_e32 v35, v36, v148
	v_exp_f32_e32 v74, v35
	v_sub_f32_e32 v35, v37, v148
	v_exp_f32_e32 v75, v35
	v_sub_f32_e32 v35, v38, v148
	v_add_f32_e32 v34, 0, v72
	v_exp_f32_e32 v76, v35
	v_sub_f32_e32 v35, v39, v148
	v_add_f32_e32 v34, v73, v34
	v_exp_f32_e32 v77, v35
	v_sub_f32_e32 v35, v40, v148
	v_add_f32_e32 v34, v74, v34
	v_exp_f32_e32 v78, v35
	v_sub_f32_e32 v35, v41, v148
	v_add_f32_e32 v34, v75, v34
	v_exp_f32_e32 v79, v35
	v_sub_f32_e32 v35, v42, v148
	v_add_f32_e32 v34, v76, v34
	v_exp_f32_e32 v80, v35
	v_sub_f32_e32 v35, v43, v148
	v_add_f32_e32 v34, v77, v34
	v_exp_f32_e32 v81, v35
	v_sub_f32_e32 v35, v44, v148
	v_add_f32_e32 v34, v78, v34
	v_exp_f32_e32 v82, v35
	v_sub_f32_e32 v35, v45, v148
	v_add_f32_e32 v34, v79, v34
	v_exp_f32_e32 v83, v35
	v_sub_f32_e32 v35, v46, v148
	v_add_f32_e32 v34, v80, v34
	v_exp_f32_e32 v96, v35
	v_sub_f32_e32 v35, v47, v148
	v_add_f32_e32 v34, v81, v34
	v_exp_f32_e32 v97, v35
	v_sub_f32_e32 v35, v48, v148
	v_add_f32_e32 v34, v82, v34
	v_exp_f32_e32 v98, v35
	v_sub_f32_e32 v35, v49, v148
	v_add_f32_e32 v34, v83, v34
	v_exp_f32_e32 v99, v35
	v_add_f32_e32 v34, v96, v34
	v_add_f32_e32 v34, v97, v34
	v_add_f32_e32 v34, v98, v34
	v_add_f32_e32 v235, v99, v34
	v_sub_f32_e32 v34, v50, v148
	v_exp_f32_e32 v188, v34
	ds_bpermute_b32 v236, v201, v235
	v_pk_mul_f32 v[34:35], v[32:33], v[188:189] op_sel_hi:[1,0]
	v_pk_mul_f32 v[32:33], v[30:31], v[188:189] op_sel_hi:[1,0]
	v_pk_mul_f32 v[30:31], v[28:29], v[188:189] op_sel_hi:[1,0]
	v_pk_mul_f32 v[28:29], v[26:27], v[188:189] op_sel_hi:[1,0]
	v_pk_mul_f32 v[26:27], v[24:25], v[188:189] op_sel_hi:[1,0]
	v_pk_mul_f32 v[24:25], v[22:23], v[188:189] op_sel_hi:[1,0]
	v_pk_mul_f32 v[22:23], v[20:21], v[188:189] op_sel_hi:[1,0]
	v_pk_mul_f32 v[20:21], v[18:19], v[188:189] op_sel_hi:[1,0]
	v_pk_mul_f32 v[50:51], v[16:17], v[188:189] op_sel_hi:[1,0]
	v_pk_mul_f32 v[48:49], v[14:15], v[188:189] op_sel_hi:[1,0]
	v_pk_mul_f32 v[46:47], v[12:13], v[188:189] op_sel_hi:[1,0]
	v_pk_mul_f32 v[44:45], v[10:11], v[188:189] op_sel_hi:[1,0]
	v_pk_mul_f32 v[42:43], v[8:9], v[188:189] op_sel_hi:[1,0]
	v_pk_mul_f32 v[40:41], v[6:7], v[188:189] op_sel_hi:[1,0]
	v_pk_mul_f32 v[38:39], v[4:5], v[188:189] op_sel_hi:[1,0]
	v_pk_mul_f32 v[36:37], v[2:3], v[188:189] op_sel_hi:[1,0]
	v_cvt_pk_bf16_f32 v2, v72, v73
	v_cvt_pk_bf16_f32 v3, v74, v75
	v_cvt_pk_bf16_f32 v4, v76, v77
	v_cvt_pk_bf16_f32 v5, v78, v79
	v_sub_u32_e32 v18, v237, v193
	v_mov_b32_e32 v19, v214
	v_mfma_f32_32x32x16_bf16 v[20:35], v[52:55], v[2:5], v[20:35]
	s_waitcnt lgkmcnt(0)
	v_mfma_f32_32x32x16_bf16 v[36:51], v[92:95], v[2:5], v[36:51]
	v_cvt_pk_bf16_f32 v2, v80, v81
	v_cvt_pk_bf16_f32 v3, v82, v83
	v_cvt_pk_bf16_f32 v4, v96, v97
	v_cvt_pk_bf16_f32 v5, v98, v99
	s_nop 1
	v_mfma_f32_32x32x16_bf16 v[20:35], v[88:91], v[2:5], v[20:35]
	v_mfma_f32_32x32x16_bf16 v[36:51], v[84:87], v[2:5], v[36:51]
	v_mfma_f32_32x32x16_bf16 v[2:17], v[68:71], v[112:115], 0
	v_mfma_f32_32x32x16_bf16 v[2:17], v[64:67], v[108:111], v[2:17]
	v_mfma_f32_32x32x16_bf16 v[2:17], v[60:63], v[104:107], v[2:17]
	v_mfma_f32_32x32x16_bf16 v[2:17], v[56:59], v[100:103], v[2:17]
	s_nop 4
	v_cmp_ge_i32_e32 vcc, 0, v18
	v_cmp_ge_i32_e64 s[24:25], 1, v18
	v_cmp_ge_i32_e64 s[26:27], 2, v18
	v_cmp_ge_i32_e64 s[28:29], 3, v18
	v_cmp_ge_i32_e64 s[30:31], 8, v18
	v_cmp_ge_i32_e64 s[34:35], 9, v18
	s_nop 0
	v_cndmask_b32_e32 v2, v211, v2, vcc
	v_cmp_ge_i32_e32 vcc, 10, v18
	v_cndmask_b32_e64 v3, v211, v3, s[24:25]
	v_cmp_ge_i32_e64 s[24:25], 11, v18
	v_cndmask_b32_e64 v4, v211, v4, s[26:27]
	v_cmp_ge_i32_e64 s[26:27], 16, v18
	v_cndmask_b32_e64 v5, v211, v5, s[28:29]
	v_cmp_ge_i32_e64 s[28:29], 17, v18
	v_cndmask_b32_e64 v6, v211, v6, s[30:31]
	v_cmp_ge_i32_e64 s[30:31], 18, v18
	v_cndmask_b32_e64 v7, v211, v7, s[34:35]
	v_cmp_ge_i32_e64 s[34:35], 19, v18
	v_cndmask_b32_e32 v8, v211, v8, vcc
	v_cmp_ge_i32_e32 vcc, 24, v18
	v_cndmask_b32_e64 v9, v211, v9, s[24:25]
	v_cmp_ge_i32_e64 s[24:25], 25, v18
	v_cndmask_b32_e64 v10, v211, v10, s[26:27]
	v_cmp_ge_i32_e64 s[26:27], 26, v18
	v_cndmask_b32_e64 v11, v211, v11, s[28:29]
	v_cmp_ge_i32_e64 s[28:29], 27, v18
	v_cndmask_b32_e64 v12, v211, v12, s[30:31]
	v_cndmask_b32_e64 v13, v211, v13, s[34:35]
	v_cndmask_b32_e32 v14, v211, v14, vcc
	v_cndmask_b32_e64 v15, v211, v15, s[24:25]
	v_cndmask_b32_e64 v16, v211, v16, s[26:27]
	v_cndmask_b32_e64 v17, v211, v17, s[28:29]
	s_nop 0
	v_max3_f32 v18, v2, s59, v3
	v_max3_f32 v18, v18, v4, v5
	v_max3_f32 v18, v18, v6, v7
	v_max3_f32 v18, v18, v8, v9
	v_max3_f32 v18, v18, v10, v11
	v_max3_f32 v18, v18, v12, v13
	v_max3_f32 v18, v18, v14, v15
	v_max3_f32 v18, v18, v16, v17
	ds_bpermute_b32 v19, v201, v18
	s_mov_b32 s59, 0xf149f2ca
	s_waitcnt lgkmcnt(0)
; #define LAS __attribute__((address_space(3)))
; __device__ __forceinline__ void att_block(const bf16x8 (&kf)[4], const bf16x8 (&qf)[4], const bf16x8 (&va)[4], f32x16& o0, f32x16& o1, float& mrun, float& lrun, bool domask, int lo_, int hi_) {
;     ...
;     const float mnew = fmaxf(mrun, bmax);
;     float lsum = 0.f;
; #pragma unroll
;     for (int i = 0; i < 16; ++i) { st[i] = __builtin_amdgcn_exp2f(st[i] - mnew); lsum += st[i]; }
;     lsum += __shfl_xor(lsum, 32);
;     const float alpha = __builtin_amdgcn_exp2f(mrun - mnew);
;     lrun = lrun * alpha + lsum; mrun = mnew;
; #pragma unroll
;     for (int i = 0; i < 16; ++i) { o0[i] *= alpha; o1[i] *= alpha; }
; #pragma unroll
;     for (int s = 0; s < 2; ++s) { v4u w; w.x = pk2(st[8 * s], st[8 * s + 1]); w.y = pk2(st[8 * s + 2], st[8 * s + 3]); w.z = pk2(st[8 * s + 4], st[8 * s + 5]); w.w = pk2(st[8 * s + 6], st[8 * s + 7]);
;         const bf16x8 pb = __builtin_bit_cast(bf16x8, w);
;         o0 = __builtin_amdgcn_mfma_f32_32x32x16_bf16(va[2 * s], pb, o0, 0, 0, 0);
;         o1 = __builtin_amdgcn_mfma_f32_32x32x16_bf16(va[2 * s + 1], pb, o1, 0, 0, 0); }
; __device__ __forceinline__ void att_phase(unsigned char* ws, LAS unsigned char* lds, int lane, int wave, int G) {
;     ...
;         for (int kb = 0; kb < 6; ++kb) {
;             asm volatile("s_waitcnt vmcnt(0)" ::: "memory");
;             if (kb < 5) ATT_DMA_KV(P, kb + 1, sb ^ 1);
;             else if (hn) ATT_DMA_KV(N, 0, sb ^ 1);
;             bf16x8 kf[4], va[4];
; #pragma unroll
;             for (int kk = 0; kk < 4; ++kk) kf[kk] = *(LAS const bf16x8*)(kfb + sb * 4096 + (((2 * kk + h) ^ (qc & 7)) << 4));
;             LAS const unsigned char* trs = trb + 8192 + sb * 4096;
; #pragma unroll
;             for (int s = 0; s < 2; ++s) {
;                 const s16x4 lo0 = vtr(trs + (16 * s) * VP), hi0 = vtr(trs + (16 * s + 8) * VP);
;                 const s16x4 lo1 = vtr(trs + (16 * s) * VP + 64), hi1 = vtr(trs + (16 * s + 8) * VP + 64);
;                 va[2 * s] = (bf16x8){lo0[0], lo0[1], lo0[2], lo0[3], hi0[0], hi0[1], hi0[2], hi0[3]};
;                 va[2 * s + 1] = (bf16x8){lo1[0], lo1[1], lo1[2], lo1[3], hi1[0], hi1[1], hi1[2], hi1[3]};
;             }
;             if (kb <= 4) {
;                 att_block(kf, qfA, va, oA0, oA1, mA, lA, kb == 0 || kb == 4 || kminA > 32 * kb, mloA - 4 * h - 32 * kb, qc + 128 - 4 * h - 32 * kb);
	v_max3_f32 v150, v18, v19, s59
	v_sub_f32_e32 v2, v2, v150
	v_exp_f32_e32 v18, v2
	v_sub_f32_e32 v3, v3, v150
	v_exp_f32_e32 v19, v3
	v_sub_f32_e32 v3, v4, v150
	v_exp_f32_e32 v56, v3
	v_sub_f32_e32 v3, v5, v150
	v_exp_f32_e32 v57, v3
	v_sub_f32_e32 v3, v6, v150
	v_add_f32_e32 v2, 0, v18
	v_exp_f32_e32 v58, v3
	v_sub_f32_e32 v3, v7, v150
	v_add_f32_e32 v2, v19, v2
	v_exp_f32_e32 v59, v3
	v_sub_f32_e32 v3, v8, v150
	v_add_f32_e32 v2, v56, v2
	v_exp_f32_e32 v60, v3
	v_sub_f32_e32 v3, v9, v150
	v_add_f32_e32 v2, v57, v2
	v_exp_f32_e32 v61, v3
	v_sub_f32_e32 v3, v10, v150
	v_add_f32_e32 v2, v58, v2
	v_exp_f32_e32 v132, v3
	v_sub_f32_e32 v3, v11, v150
	v_add_f32_e32 v2, v59, v2
	v_exp_f32_e32 v133, v3
	v_sub_f32_e32 v3, v12, v150
	v_add_f32_e32 v2, v60, v2
	v_exp_f32_e32 v134, v3
	v_sub_f32_e32 v3, v13, v150
	v_add_f32_e32 v2, v61, v2
	v_exp_f32_e32 v135, v3
	v_sub_f32_e32 v3, v14, v150
	v_add_f32_e32 v2, v132, v2
	v_exp_f32_e32 v136, v3
	v_sub_f32_e32 v3, v15, v150
	v_add_f32_e32 v2, v133, v2
	v_exp_f32_e32 v137, v3
	v_sub_f32_e32 v3, v16, v150
	v_add_f32_e32 v2, v134, v2
	v_exp_f32_e32 v138, v3
	v_sub_f32_e32 v3, v17, v150
	v_add_f32_e32 v2, v135, v2
	v_exp_f32_e32 v139, v3
	v_add_f32_e32 v2, v136, v2
	v_add_f32_e32 v2, v137, v2
	v_add_f32_e32 v2, v138, v2
	v_add_f32_e32 v233, v139, v2
	v_sub_f32_e32 v2, 0xf149f2ca, v150
	v_exp_f32_e32 v2, v2
	v_cvt_pk_bf16_f32 v96, v18, v19
	v_cvt_pk_bf16_f32 v97, v56, v57
	v_cvt_pk_bf16_f32 v98, v58, v59
	v_mul_f32_e32 v2, 0, v2
	v_mov_b32_e32 v3, v2
	v_mov_b32_e32 v4, v2
	v_mov_b32_e32 v5, v2
	v_mov_b32_e32 v6, v2
	v_mov_b32_e32 v7, v2
	v_mov_b32_e32 v8, v2
	v_mov_b32_e32 v9, v2
	v_mov_b32_e32 v10, v2
	v_mov_b32_e32 v11, v2
	v_mov_b32_e32 v12, v2
	v_mov_b32_e32 v13, v2
	v_mov_b32_e32 v14, v2
	v_mov_b32_e32 v15, v2
	v_mov_b32_e32 v16, v2
	v_mov_b32_e32 v17, v2
	v_cvt_pk_bf16_f32 v99, v60, v61
	ds_bpermute_b32 v234, v201, v233
	s_nop 0
	v_mfma_f32_32x32x16_bf16 v[68:83], v[52:55], v[96:99], v[2:17]
	v_mov_b64_e32 v[66:67], v[16:17]
	v_mov_b64_e32 v[64:65], v[14:15]
	v_mov_b64_e32 v[62:63], v[12:13]
	v_mov_b64_e32 v[60:61], v[10:11]
	v_mov_b64_e32 v[58:59], v[8:9]
	v_mov_b64_e32 v[56:57], v[6:7]
	v_mov_b64_e32 v[54:55], v[4:5]
	v_mov_b64_e32 v[52:53], v[2:3]
	v_cvt_pk_bf16_f32 v4, v132, v133
	v_cvt_pk_bf16_f32 v5, v134, v135
	v_mfma_f32_32x32x16_bf16 v[52:67], v[92:95], v[96:99], v[52:67]
	v_cvt_pk_bf16_f32 v6, v136, v137
	v_cvt_pk_bf16_f32 v7, v138, v139
	s_nop 1
	v_mfma_f32_32x32x16_bf16 v[68:83], v[88:91], v[4:7], v[68:83]
	v_mfma_f32_32x32x16_bf16 v[52:67], v[84:87], v[4:7], v[52:67]
	v_mul_lo_u32 v3, s56, v217
	v_add_u32_e32 v3, s11, v3
	v_max_i32_e32 v164, 0, v3
	v_lshl_add_u64 v[4:5], s[12:13], 0, v[164:165]
	v_lshlrev_b64 v[4:5], 7, v[4:5]
	s_mov_b32 m0, s57
	s_waitcnt vmcnt(0)
	v_lshl_add_u64 v[6:7], v[180:181], 0, v[4:5]
	v_add_u32_e32 v3, s6, v3
	global_load_lds_dwordx4 v[6:7], off
	v_lshl_add_u64 v[4:5], v[182:183], 0, v[4:5]
	s_mov_b32 m0, s7
	v_max_i32_e32 v164, 0, v3
	global_load_lds_dwordx4 v[4:5], off
	v_lshl_add_u64 v[4:5], s[12:13], 0, v[164:165]
	v_lshlrev_b64 v[4:5], 7, v[4:5]
	v_readlane_b32 s59, v254, 28
	v_lshl_add_u64 v[6:7], v[180:181], 0, v[4:5]
	s_mov_b32 m0, s59
	v_readlane_b32 s59, v254, 29
	v_add_u32_e32 v3, s6, v3
	global_load_lds_dwordx4 v[6:7], off
	v_lshl_add_u64 v[4:5], v[182:183], 0, v[4:5]
	s_mov_b32 m0, s59
	v_max_i32_e32 v164, 0, v3
	global_load_lds_dwordx4 v[4:5], off
	v_lshl_add_u64 v[4:5], s[12:13], 0, v[164:165]
	v_lshlrev_b64 v[4:5], 7, v[4:5]
	v_lshl_add_u64 v[6:7], v[180:181], 0, v[4:5]
	s_mov_b32 m0, s15
	v_add_u32_e32 v3, s6, v3
	global_load_lds_dwordx4 v[6:7], off
	v_lshl_add_u64 v[4:5], v[182:183], 0, v[4:5]
	s_mov_b32 m0, s17
	v_max_i32_e32 v164, 0, v3
	global_load_lds_dwordx4 v[4:5], off
	v_lshl_add_u64 v[4:5], s[12:13], 0, v[164:165]
	v_lshlrev_b64 v[4:5], 7, v[4:5]
	v_lshl_add_u64 v[6:7], v[180:181], 0, v[4:5]
	s_mov_b32 m0, s21
	v_readlane_b32 s59, v254, 30
	global_load_lds_dwordx4 v[6:7], off
	v_lshl_add_u64 v[4:5], v[182:183], 0, v[4:5]
	s_mov_b32 m0, s59
	s_cmpk_lt_i32 s58, 0x41
	global_load_lds_dwordx4 v[4:5], off
	ds_read_b128 v[144:147], v225
	ds_read_b128 v[140:143], v226
	s_waitcnt lgkmcnt(0)
	v_mfma_f32_32x32x16_bf16 v[4:19], v[144:147], v[128:131], 0
	ds_read_b128 v[136:139], v227
	ds_read_b128 v[132:135], v228
	s_waitcnt vmcnt(0)
	ds_read_b64_tr_b16 v[96:97], v229 offset:8192
	ds_read_b64_tr_b16 v[98:99], v229 offset:9216
	ds_read_b64_tr_b16 v[94:95], v229 offset:9280
	ds_read_b64_tr_b16 v[92:93], v229 offset:8256
	ds_read_b64_tr_b16 v[88:89], v229 offset:10240
	ds_read_b64_tr_b16 v[90:91], v229 offset:11264
	ds_read_b64_tr_b16 v[86:87], v229 offset:11328
	ds_read_b64_tr_b16 v[84:85], v229 offset:10304
	v_mfma_f32_32x32x16_bf16 v[4:19], v[140:143], v[124:127], v[4:19]
	s_waitcnt lgkmcnt(9)
	v_mfma_f32_32x32x16_bf16 v[4:19], v[136:139], v[120:123], v[4:19]
	s_waitcnt lgkmcnt(8)
	v_mfma_f32_32x32x16_bf16 v[4:19], v[132:135], v[116:119], v[4:19]
	s_cbranch_scc1 .LBB0_84
	v_sub_u32_e32 v3, v199, v218
	v_mov_b32_e32 v149, v219
	s_nop 0
	s_nop 1
	v_cmp_ge_i32_e32 vcc, 0, v3
	v_cmp_ge_i32_e64 s[24:25], 1, v3
	v_cmp_ge_i32_e64 s[26:27], 2, v3
	v_cmp_ge_i32_e64 s[28:29], 3, v3
	v_cmp_ge_i32_e64 s[30:31], 8, v3
	v_cmp_ge_i32_e64 s[34:35], 9, v3
	v_cndmask_b32_e32 v4, v211, v4, vcc
	v_cmp_ge_i32_e32 vcc, 10, v3
	v_cndmask_b32_e64 v5, v211, v5, s[24:25]
	v_cmp_ge_i32_e64 s[24:25], 11, v3
	v_cndmask_b32_e64 v6, v211, v6, s[26:27]
	v_cmp_ge_i32_e64 s[26:27], 16, v3
	v_cndmask_b32_e64 v7, v211, v7, s[28:29]
	v_cmp_ge_i32_e64 s[28:29], 17, v3
	v_cndmask_b32_e64 v8, v211, v8, s[30:31]
	v_cmp_ge_i32_e64 s[30:31], 18, v3
	v_cndmask_b32_e64 v9, v211, v9, s[34:35]
	v_cmp_ge_i32_e64 s[34:35], 19, v3
	v_cndmask_b32_e32 v10, v211, v10, vcc
	v_cmp_ge_i32_e32 vcc, 24, v3
	v_cndmask_b32_e64 v11, v211, v11, s[24:25]
	v_cmp_ge_i32_e64 s[24:25], 25, v3
	v_cndmask_b32_e64 v12, v211, v12, s[26:27]
	v_cmp_ge_i32_e64 s[26:27], 26, v3
	v_cndmask_b32_e64 v13, v211, v13, s[28:29]
	v_cmp_ge_i32_e64 s[28:29], 27, v3
	v_cndmask_b32_e64 v14, v211, v14, s[30:31]
	v_cndmask_b32_e64 v15, v211, v15, s[34:35]
	v_cndmask_b32_e32 v16, v211, v16, vcc
	v_cndmask_b32_e64 v17, v211, v17, s[24:25]
	v_cndmask_b32_e64 v18, v211, v18, s[26:27]
	v_cndmask_b32_e64 v19, v211, v19, s[28:29]
	s_nop 0
	s_nop 1
; __device__ __forceinline__ unsigned pk2(float lo, float hi) { return pg8::cvt_pk_bf16(lo, hi); }
; __device__ __forceinline__ void att_block(const bf16x8 (&kf)[4], const bf16x8 (&qf)[4], const bf16x8 (&va)[4], f32x16& o0, f32x16& o1, float& mrun, float& lrun, bool domask, int lo_, int hi_) {
;     ...
;         for (int i = 0; i < 16; ++i) { const int ci = (i & 3) + 8 * (i >> 2); st[i] = ((ci - lo_) | (hi_ - ci)) < 0 ? -INFINITY : st[i]; }
;     }
;     float bmax = -INFINITY;
; #pragma unroll
;     for (int i = 0; i < 16; ++i) bmax = fmaxf(bmax, st[i]);
;     bmax = fmaxf(bmax, __shfl_xor(bmax, 32));
;     const float mnew = fmaxf(mrun, bmax);
;     float lsum = 0.f;
; #pragma unroll
;     for (int i = 0; i < 16; ++i) { st[i] = __builtin_amdgcn_exp2f(st[i] - mnew); lsum += st[i]; }
;     lsum += __shfl_xor(lsum, 32);
;     const float alpha = __builtin_amdgcn_exp2f(mrun - mnew);
;     lrun = lrun * alpha + lsum; mrun = mnew;
; #pragma unroll
;     for (int i = 0; i < 16; ++i) { o0[i] *= alpha; o1[i] *= alpha; }
; #pragma unroll
;     for (int s = 0; s < 2; ++s) { v4u w; w.x = pk2(st[8 * s], st[8 * s + 1]); w.y = pk2(st[8 * s + 2], st[8 * s + 3]); w.z = pk2(st[8 * s + 4], st[8 * s + 5]); w.w = pk2(st[8 * s + 6], st[8 * s + 7]);
;         const bf16x8 pb = __builtin_bit_cast(bf16x8, w);
;         o0 = __builtin_amdgcn_mfma_f32_32x32x16_bf16(va[2 * s], pb, o0, 0, 0, 0);
;         o1 = __builtin_amdgcn_mfma_f32_32x32x16_bf16(va[2 * s + 1], pb, o1, 0, 0, 0); }
.LBB0_84:
	s_nop 10
	v_max3_f32 v3, v4, s60, v5
	v_max3_f32 v3, v3, v6, v7
	v_max3_f32 v3, v3, v8, v9
	v_max3_f32 v3, v3, v10, v11
	v_max3_f32 v3, v3, v12, v13
	v_max3_f32 v3, v3, v14, v15
	v_max3_f32 v3, v3, v16, v17
	v_max3_f32 v3, v3, v18, v19
	ds_bpermute_b32 v149, v201, v3
	s_cmp_lt_i32 s14, 33
	s_waitcnt lgkmcnt(0)
	v_max3_f32 v149, v148, v3, v149
	v_sub_f32_e32 v3, v4, v149
	v_exp_f32_e32 v3, v3
	v_sub_f32_e32 v5, v5, v149
	v_exp_f32_e32 v151, v5
	v_sub_f32_e32 v5, v6, v149
	v_exp_f32_e32 v152, v5
	v_sub_f32_e32 v5, v7, v149
	v_exp_f32_e32 v153, v5
	v_sub_f32_e32 v5, v8, v149
	v_add_f32_e32 v4, 0, v3
	v_exp_f32_e32 v154, v5
	v_sub_f32_e32 v5, v9, v149
	v_add_f32_e32 v4, v151, v4
	v_exp_f32_e32 v155, v5
	v_sub_f32_e32 v5, v10, v149
	v_add_f32_e32 v4, v152, v4
	v_exp_f32_e32 v156, v5
	v_sub_f32_e32 v5, v11, v149
	v_add_f32_e32 v4, v153, v4
	v_exp_f32_e32 v157, v5
	v_sub_f32_e32 v5, v12, v149
	v_add_f32_e32 v4, v154, v4
	v_exp_f32_e32 v158, v5
	v_sub_f32_e32 v5, v13, v149
	v_add_f32_e32 v4, v155, v4
	v_exp_f32_e32 v159, v5
	v_sub_f32_e32 v5, v14, v149
	v_add_f32_e32 v4, v156, v4
	v_exp_f32_e32 v160, v5
	v_sub_f32_e32 v5, v15, v149
	v_add_f32_e32 v4, v157, v4
	v_exp_f32_e32 v161, v5
	v_sub_f32_e32 v5, v16, v149
	v_add_f32_e32 v4, v158, v4
	v_exp_f32_e32 v162, v5
	v_sub_f32_e32 v5, v17, v149
	v_add_f32_e32 v4, v159, v4
	v_exp_f32_e32 v163, v5
	v_sub_f32_e32 v5, v18, v149
	v_add_f32_e32 v4, v160, v4
	v_exp_f32_e32 v164, v5
	v_sub_f32_e32 v5, v19, v149
	v_add_f32_e32 v4, v161, v4
	v_exp_f32_e32 v166, v5
	v_add_f32_e32 v4, v162, v4
	v_add_f32_e32 v4, v163, v4
	v_add_f32_e32 v4, v164, v4
	v_add_f32_e32 v239, v166, v4
	v_sub_f32_e32 v4, v148, v149
	v_exp_f32_e32 v192, v4
	ds_bpermute_b32 v240, v201, v239
	v_pk_mul_f32 v[18:19], v[34:35], v[192:193] op_sel_hi:[1,0]
	v_pk_mul_f32 v[16:17], v[32:33], v[192:193] op_sel_hi:[1,0]
	v_pk_mul_f32 v[14:15], v[30:31], v[192:193] op_sel_hi:[1,0]
	v_pk_mul_f32 v[12:13], v[28:29], v[192:193] op_sel_hi:[1,0]
	v_pk_mul_f32 v[10:11], v[26:27], v[192:193] op_sel_hi:[1,0]
	v_pk_mul_f32 v[8:9], v[24:25], v[192:193] op_sel_hi:[1,0]
	v_pk_mul_f32 v[6:7], v[22:23], v[192:193] op_sel_hi:[1,0]
	v_pk_mul_f32 v[4:5], v[20:21], v[192:193] op_sel_hi:[1,0]
	v_pk_mul_f32 v[34:35], v[50:51], v[192:193] op_sel_hi:[1,0]
	v_pk_mul_f32 v[32:33], v[48:49], v[192:193] op_sel_hi:[1,0]
	v_pk_mul_f32 v[30:31], v[46:47], v[192:193] op_sel_hi:[1,0]
	v_pk_mul_f32 v[28:29], v[44:45], v[192:193] op_sel_hi:[1,0]
	v_pk_mul_f32 v[26:27], v[42:43], v[192:193] op_sel_hi:[1,0]
	v_pk_mul_f32 v[24:25], v[40:41], v[192:193] op_sel_hi:[1,0]
	v_pk_mul_f32 v[22:23], v[38:39], v[192:193] op_sel_hi:[1,0]
	v_pk_mul_f32 v[20:21], v[36:37], v[192:193] op_sel_hi:[1,0]
	v_cvt_pk_bf16_f32 v36, v3, v151
	v_cvt_pk_bf16_f32 v37, v152, v153
	v_cvt_pk_bf16_f32 v38, v154, v155
	v_cvt_pk_bf16_f32 v39, v156, v157
	s_nop 1
	v_mfma_f32_32x32x16_bf16 v[4:19], v[96:99], v[36:39], v[4:19]
	v_mfma_f32_32x32x16_bf16 v[20:35], v[92:95], v[36:39], v[20:35]
	v_cvt_pk_bf16_f32 v36, v158, v159
	v_cvt_pk_bf16_f32 v37, v160, v161
	v_cvt_pk_bf16_f32 v38, v162, v163
	v_cvt_pk_bf16_f32 v39, v164, v166
	s_nop 1
	v_mfma_f32_32x32x16_bf16 v[4:19], v[88:91], v[36:39], v[4:19]
	v_mfma_f32_32x32x16_bf16 v[20:35], v[84:87], v[36:39], v[20:35]
	v_mfma_f32_32x32x16_bf16 v[36:51], v[144:147], v[112:115], 0
	v_mfma_f32_32x32x16_bf16 v[36:51], v[140:143], v[108:111], v[36:51]
	v_mfma_f32_32x32x16_bf16 v[36:51], v[136:139], v[104:107], v[36:51]
	v_mfma_f32_32x32x16_bf16 v[36:51], v[132:135], v[100:103], v[36:51]
	s_cbranch_scc1 .LBB0_86
	v_sub_u32_e32 v3, v237, v215
	v_mov_b32_e32 v132, v216
	s_nop 0
	s_nop 1
	v_cmp_ge_i32_e32 vcc, 0, v3
	v_cmp_ge_i32_e64 s[24:25], 1, v3
	v_cmp_ge_i32_e64 s[26:27], 2, v3
	v_cmp_ge_i32_e64 s[28:29], 3, v3
	v_cmp_ge_i32_e64 s[30:31], 8, v3
	v_cmp_ge_i32_e64 s[34:35], 9, v3
	v_cndmask_b32_e32 v36, v211, v36, vcc
	v_cmp_ge_i32_e32 vcc, 10, v3
	v_cndmask_b32_e64 v37, v211, v37, s[24:25]
	v_cmp_ge_i32_e64 s[24:25], 11, v3
	v_cndmask_b32_e64 v38, v211, v38, s[26:27]
	v_cmp_ge_i32_e64 s[26:27], 16, v3
	v_cndmask_b32_e64 v39, v211, v39, s[28:29]
	v_cmp_ge_i32_e64 s[28:29], 17, v3
	v_cndmask_b32_e64 v40, v211, v40, s[30:31]
	v_cmp_ge_i32_e64 s[30:31], 18, v3
	v_cndmask_b32_e64 v41, v211, v41, s[34:35]
	v_cmp_ge_i32_e64 s[34:35], 19, v3
	v_cndmask_b32_e32 v42, v211, v42, vcc
	v_cmp_ge_i32_e32 vcc, 24, v3
	v_cndmask_b32_e64 v43, v211, v43, s[24:25]
	v_cmp_ge_i32_e64 s[24:25], 25, v3
	v_cndmask_b32_e64 v44, v211, v44, s[26:27]
	v_cmp_ge_i32_e64 s[26:27], 26, v3
	v_cndmask_b32_e64 v45, v211, v45, s[28:29]
	v_cmp_ge_i32_e64 s[28:29], 27, v3
	v_cndmask_b32_e64 v46, v211, v46, s[30:31]
	v_cndmask_b32_e64 v47, v211, v47, s[34:35]
	v_cndmask_b32_e32 v48, v211, v48, vcc
	v_cndmask_b32_e64 v49, v211, v49, s[24:25]
	v_cndmask_b32_e64 v50, v211, v50, s[26:27]
	v_cndmask_b32_e64 v51, v211, v51, s[28:29]
	s_nop 0
	s_nop 1
; #define LAS __attribute__((address_space(3)))
; __device__ __forceinline__ void att_block(const bf16x8 (&kf)[4], const bf16x8 (&qf)[4], const bf16x8 (&va)[4], f32x16& o0, f32x16& o1, float& mrun, float& lrun, bool domask, int lo_, int hi_) {
;     ...
;     const float mnew = fmaxf(mrun, bmax);
;     float lsum = 0.f;
; #pragma unroll
;     for (int i = 0; i < 16; ++i) { st[i] = __builtin_amdgcn_exp2f(st[i] - mnew); lsum += st[i]; }
;     lsum += __shfl_xor(lsum, 32);
;     const float alpha = __builtin_amdgcn_exp2f(mrun - mnew);
;     lrun = lrun * alpha + lsum; mrun = mnew;
; #pragma unroll
;     for (int i = 0; i < 16; ++i) { o0[i] *= alpha; o1[i] *= alpha; }
; #pragma unroll
;     for (int s = 0; s < 2; ++s) { v4u w; w.x = pk2(st[8 * s], st[8 * s + 1]); w.y = pk2(st[8 * s + 2], st[8 * s + 3]); w.z = pk2(st[8 * s + 4], st[8 * s + 5]); w.w = pk2(st[8 * s + 6], st[8 * s + 7]);
;         const bf16x8 pb = __builtin_bit_cast(bf16x8, w);
;         o0 = __builtin_amdgcn_mfma_f32_32x32x16_bf16(va[2 * s], pb, o0, 0, 0, 0);
;         o1 = __builtin_amdgcn_mfma_f32_32x32x16_bf16(va[2 * s + 1], pb, o1, 0, 0, 0); }
; __device__ __forceinline__ void att_phase(unsigned char* ws, LAS unsigned char* lds, int lane, int wave, int G) {
;     ...
;         for (int kb = 0; kb < 6; ++kb) {
;             asm volatile("s_waitcnt vmcnt(0)" ::: "memory");
;             if (kb < 5) ATT_DMA_KV(P, kb + 1, sb ^ 1);
;             else if (hn) ATT_DMA_KV(N, 0, sb ^ 1);
;             bf16x8 kf[4], va[4];
; #pragma unroll
;             for (int kk = 0; kk < 4; ++kk) kf[kk] = *(LAS const bf16x8*)(kfb + sb * 4096 + (((2 * kk + h) ^ (qc & 7)) << 4));
;             LAS const unsigned char* trs = trb + 8192 + sb * 4096;
; #pragma unroll
;             for (int s = 0; s < 2; ++s) {
;                 const s16x4 lo0 = vtr(trs + (16 * s) * VP), hi0 = vtr(trs + (16 * s + 8) * VP);
;                 const s16x4 lo1 = vtr(trs + (16 * s) * VP + 64), hi1 = vtr(trs + (16 * s + 8) * VP + 64);
;                 va[2 * s] = (bf16x8){lo0[0], lo0[1], lo0[2], lo0[3], hi0[0], hi0[1], hi0[2], hi0[3]};
;                 va[2 * s + 1] = (bf16x8){lo1[0], lo1[1], lo1[2], lo1[3], hi1[0], hi1[1], hi1[2], hi1[3]};
;             }
;             if (kb <= 4) {
;                 att_block(kf, qfA, va, oA0, oA1, mA, lA, kb == 0 || kb == 4 || kminA > 32 * kb, mloA - 4 * h - 32 * kb, qc + 128 - 4 * h - 32 * kb);
.LBB0_86:
	s_nop 10
	v_max3_f32 v3, v36, s60, v37
	v_max3_f32 v3, v3, v38, v39
	v_max3_f32 v3, v3, v40, v41
	v_max3_f32 v3, v3, v42, v43
	v_max3_f32 v3, v3, v44, v45
	v_max3_f32 v3, v3, v46, v47
	v_max3_f32 v3, v3, v48, v49
	v_max3_f32 v3, v3, v50, v51
	ds_bpermute_b32 v132, v201, v3
	s_waitcnt lgkmcnt(0)
	s_waitcnt lgkmcnt(0)
	v_max3_f32 v148, v150, v3, v132
	v_sub_f32_e32 v3, v36, v148
	v_sub_f32_e32 v36, v37, v148
	v_exp_f32_e32 v133, v36
	v_sub_f32_e32 v36, v38, v148
	v_exp_f32_e32 v134, v36
	v_sub_f32_e32 v36, v39, v148
	v_exp_f32_e32 v135, v36
	v_sub_f32_e32 v36, v40, v148
	v_exp_f32_e32 v136, v36
	v_sub_f32_e32 v36, v41, v148
	v_exp_f32_e32 v137, v36
	v_sub_f32_e32 v36, v42, v148
	v_exp_f32_e32 v138, v36
	v_sub_f32_e32 v36, v43, v148
	v_exp_f32_e32 v139, v36
	v_sub_f32_e32 v36, v44, v148
	v_exp_f32_e32 v140, v36
	v_sub_f32_e32 v36, v45, v148
	v_exp_f32_e32 v141, v36
	v_sub_f32_e32 v36, v46, v148
	v_exp_f32_e32 v142, v36
	v_sub_f32_e32 v36, v47, v148
	v_exp_f32_e32 v143, v36
	v_sub_f32_e32 v36, v48, v148
	v_exp_f32_e32 v132, v3
	v_exp_f32_e32 v144, v36
	v_sub_f32_e32 v36, v49, v148
	v_exp_f32_e32 v145, v36
	v_sub_f32_e32 v36, v50, v148
	v_exp_f32_e32 v146, v36
	v_sub_f32_e32 v36, v51, v148
	v_exp_f32_e32 v147, v36
	v_sub_f32_e32 v36, v150, v148
	v_add_f32_e32 v3, 0, v132
	v_exp_f32_e32 v190, v36
	v_add_f32_e32 v3, v133, v3
	v_add_f32_e32 v3, v134, v3
	v_add_f32_e32 v3, v135, v3
	v_add_f32_e32 v3, v136, v3
	v_pk_mul_f32 v[50:51], v[82:83], v[190:191] op_sel_hi:[1,0]
	v_pk_mul_f32 v[48:49], v[80:81], v[190:191] op_sel_hi:[1,0]
	v_pk_mul_f32 v[46:47], v[78:79], v[190:191] op_sel_hi:[1,0]
	v_pk_mul_f32 v[44:45], v[76:77], v[190:191] op_sel_hi:[1,0]
	v_pk_mul_f32 v[42:43], v[74:75], v[190:191] op_sel_hi:[1,0]
	v_pk_mul_f32 v[40:41], v[72:73], v[190:191] op_sel_hi:[1,0]
	v_pk_mul_f32 v[38:39], v[70:71], v[190:191] op_sel_hi:[1,0]
	v_pk_mul_f32 v[36:37], v[68:69], v[190:191] op_sel_hi:[1,0]
	v_pk_mul_f32 v[66:67], v[66:67], v[190:191] op_sel_hi:[1,0]
	v_pk_mul_f32 v[64:65], v[64:65], v[190:191] op_sel_hi:[1,0]
	v_pk_mul_f32 v[62:63], v[62:63], v[190:191] op_sel_hi:[1,0]
	v_pk_mul_f32 v[60:61], v[60:61], v[190:191] op_sel_hi:[1,0]
	v_pk_mul_f32 v[58:59], v[58:59], v[190:191] op_sel_hi:[1,0]
	v_pk_mul_f32 v[56:57], v[56:57], v[190:191] op_sel_hi:[1,0]
	v_pk_mul_f32 v[54:55], v[54:55], v[190:191] op_sel_hi:[1,0]
	v_pk_mul_f32 v[52:53], v[52:53], v[190:191] op_sel_hi:[1,0]
	v_cvt_pk_bf16_f32 v68, v132, v133
	v_cvt_pk_bf16_f32 v69, v134, v135
	v_cvt_pk_bf16_f32 v70, v136, v137
	v_cvt_pk_bf16_f32 v71, v138, v139
	v_add_f32_e32 v3, v137, v3
	v_add_f32_e32 v3, v138, v3
	v_mfma_f32_32x32x16_bf16 v[36:51], v[96:99], v[68:71], v[36:51]
	v_add_f32_e32 v3, v139, v3
	v_add_f32_e32 v3, v140, v3
	v_add_f32_e32 v3, v141, v3
	v_add_f32_e32 v3, v142, v3
	v_add_f32_e32 v3, v143, v3
	v_add_f32_e32 v3, v144, v3
	v_add_f32_e32 v3, v145, v3
	v_mfma_f32_32x32x16_bf16 v[52:67], v[92:95], v[68:71], v[52:67]
	v_cvt_pk_bf16_f32 v68, v140, v141
	v_cvt_pk_bf16_f32 v69, v142, v143
	v_cvt_pk_bf16_f32 v70, v144, v145
	v_cvt_pk_bf16_f32 v71, v146, v147
	v_add_f32_e32 v3, v146, v3
	v_add_f32_e32 v3, v147, v3
	ds_bpermute_b32 v238, v201, v3
	v_mfma_f32_32x32x16_bf16 v[36:51], v[88:91], v[68:71], v[36:51]
	v_mfma_f32_32x32x16_bf16 v[52:67], v[84:87], v[68:71], v[52:67]
	v_mul_lo_u32 v68, s56, v191
	v_add_u32_e32 v72, s11, v68
	v_max_i32_e32 v164, 0, v72
	v_lshl_add_u64 v[68:69], s[12:13], 0, v[164:165]
	v_lshlrev_b64 v[68:69], 7, v[68:69]
	s_mov_b32 m0, s33
	s_waitcnt vmcnt(0)
	v_lshl_add_u64 v[70:71], v[180:181], 0, v[68:69]
	v_add_u32_e32 v72, s6, v72
	global_load_lds_dwordx4 v[70:71], off
	v_lshl_add_u64 v[68:69], v[182:183], 0, v[68:69]
	s_mov_b32 m0, s44
	v_max_i32_e32 v164, 0, v72
	global_load_lds_dwordx4 v[68:69], off
	v_lshl_add_u64 v[68:69], s[12:13], 0, v[164:165]
	v_lshlrev_b64 v[68:69], 7, v[68:69]
	v_lshl_add_u64 v[70:71], v[180:181], 0, v[68:69]
	s_mov_b32 m0, s66
	v_add_u32_e32 v72, s6, v72
	global_load_lds_dwordx4 v[70:71], off
	v_lshl_add_u64 v[68:69], v[182:183], 0, v[68:69]
	s_mov_b32 m0, s67
	v_max_i32_e32 v164, 0, v72
	global_load_lds_dwordx4 v[68:69], off
	v_lshl_add_u64 v[68:69], s[12:13], 0, v[164:165]
	v_lshlrev_b64 v[68:69], 7, v[68:69]
	v_lshl_add_u64 v[70:71], v[180:181], 0, v[68:69]
	s_mov_b32 m0, s48
	v_lshl_add_u64 v[68:69], v[182:183], 0, v[68:69]
	global_load_lds_dwordx4 v[70:71], off
	s_mov_b32 m0, s49
	v_readlane_b32 s59, v254, 27
	global_load_lds_dwordx4 v[68:69], off
	v_add_u32_e32 v68, s6, v72
	v_max_i32_e32 v164, 0, v68
	v_lshl_add_u64 v[68:69], s[12:13], 0, v[164:165]
	v_lshlrev_b64 v[68:69], 7, v[68:69]
	v_lshl_add_u64 v[70:71], v[180:181], 0, v[68:69]
	s_mov_b32 m0, s72
	v_lshl_add_u64 v[68:69], v[182:183], 0, v[68:69]
	global_load_lds_dwordx4 v[70:71], off
	s_mov_b32 m0, s59
	s_cmpk_lt_i32 s58, 0x61
	global_load_lds_dwordx4 v[68:69], off
	ds_read_b128 v[96:99], v225 offset:4096
	ds_read_b128 v[92:95], v226 offset:4096
	s_waitcnt lgkmcnt(0)
	v_mfma_f32_32x32x16_bf16 v[68:83], v[96:99], v[128:131], 0
	ds_read_b128 v[88:91], v227 offset:4096
	ds_read_b128 v[84:87], v228 offset:4096
	s_waitcnt vmcnt(0)
	ds_read_b64_tr_b16 v[144:145], v229 offset:12288
	ds_read_b64_tr_b16 v[146:147], v229 offset:13312
	ds_read_b64_tr_b16 v[142:143], v229 offset:13376
	ds_read_b64_tr_b16 v[140:141], v229 offset:12352
	ds_read_b64_tr_b16 v[136:137], v229 offset:14336
	ds_read_b64_tr_b16 v[138:139], v229 offset:15360
	ds_read_b64_tr_b16 v[134:135], v229 offset:15424
	ds_read_b64_tr_b16 v[132:133], v229 offset:14400
	v_mfma_f32_32x32x16_bf16 v[68:83], v[92:95], v[124:127], v[68:83]
	s_waitcnt lgkmcnt(9)
	v_mfma_f32_32x32x16_bf16 v[68:83], v[88:91], v[120:123], v[68:83]
	s_waitcnt lgkmcnt(8)
	v_mfma_f32_32x32x16_bf16 v[68:83], v[84:87], v[116:119], v[68:83]
	s_cbranch_scc1 .LBB0_88
; __device__ __forceinline__ unsigned pk2(float lo, float hi) { return pg8::cvt_pk_bf16(lo, hi); }
; __device__ __forceinline__ void att_block(const bf16x8 (&kf)[4], const bf16x8 (&qf)[4], const bf16x8 (&va)[4], f32x16& o0, f32x16& o1, float& mrun, float& lrun, bool domask, int lo_, int hi_) {
;     ...
;     if (domask) {
;         asm volatile("" : "+v"(lo_), "+v"(hi_));
; #pragma unroll
;         for (int i = 0; i < 16; ++i) { const int ci = (i & 3) + 8 * (i >> 2); st[i] = ((ci - lo_) | (hi_ - ci)) < 0 ? -INFINITY : st[i]; }
;     }
;     float bmax = -INFINITY;
; #pragma unroll
;     for (int i = 0; i < 16; ++i) bmax = fmaxf(bmax, st[i]);
;     bmax = fmaxf(bmax, __shfl_xor(bmax, 32));
;     const float mnew = fmaxf(mrun, bmax);
;     float lsum = 0.f;
; #pragma unroll
;     for (int i = 0; i < 16; ++i) { st[i] = __builtin_amdgcn_exp2f(st[i] - mnew); lsum += st[i]; }
;     lsum += __shfl_xor(lsum, 32);
;     const float alpha = __builtin_amdgcn_exp2f(mrun - mnew);
;     lrun = lrun * alpha + lsum; mrun = mnew;
; #pragma unroll
;     for (int i = 0; i < 16; ++i) { o0[i] *= alpha; o1[i] *= alpha; }
; #pragma unroll
;     for (int s = 0; s < 2; ++s) { v4u w; w.x = pk2(st[8 * s], st[8 * s + 1]); w.y = pk2(st[8 * s + 2], st[8 * s + 3]); w.z = pk2(st[8 * s + 4], st[8 * s + 5]); w.w = pk2(st[8 * s + 6], st[8 * s + 7]);
;         const bf16x8 pb = __builtin_bit_cast(bf16x8, w);
;         o0 = __builtin_amdgcn_mfma_f32_32x32x16_bf16(va[2 * s], pb, o0, 0, 0, 0);
;         o1 = __builtin_amdgcn_mfma_f32_32x32x16_bf16(va[2 * s + 1], pb, o1, 0, 0, 0); }
	v_sub_u32_e32 v150, v199, v220
	v_mov_b32_e32 v151, v221
	s_nop 0
	s_nop 1
	v_cmp_ge_i32_e32 vcc, 0, v150
	v_cmp_ge_i32_e64 s[24:25], 1, v150
	v_cmp_ge_i32_e64 s[26:27], 2, v150
	v_cmp_ge_i32_e64 s[28:29], 3, v150
	v_cmp_ge_i32_e64 s[30:31], 8, v150
	v_cmp_ge_i32_e64 s[34:35], 9, v150
	v_cndmask_b32_e32 v68, v211, v68, vcc
	v_cmp_ge_i32_e32 vcc, 10, v150
	v_cndmask_b32_e64 v69, v211, v69, s[24:25]
	v_cmp_ge_i32_e64 s[24:25], 11, v150
	v_cndmask_b32_e64 v70, v211, v70, s[26:27]
	v_cmp_ge_i32_e64 s[26:27], 16, v150
	v_cndmask_b32_e64 v71, v211, v71, s[28:29]
	v_cmp_ge_i32_e64 s[28:29], 17, v150
	v_cndmask_b32_e64 v72, v211, v72, s[30:31]
	v_cmp_ge_i32_e64 s[30:31], 18, v150
	v_cndmask_b32_e64 v73, v211, v73, s[34:35]
	v_cmp_ge_i32_e64 s[34:35], 19, v150
	v_cndmask_b32_e32 v74, v211, v74, vcc
	v_cmp_ge_i32_e32 vcc, 24, v150
	v_cndmask_b32_e64 v75, v211, v75, s[24:25]
	v_cmp_ge_i32_e64 s[24:25], 25, v150
	v_cndmask_b32_e64 v76, v211, v76, s[26:27]
	v_cmp_ge_i32_e64 s[26:27], 26, v150
	v_cndmask_b32_e64 v77, v211, v77, s[28:29]
	v_cmp_ge_i32_e64 s[28:29], 27, v150
	v_cndmask_b32_e64 v78, v211, v78, s[30:31]
	v_cndmask_b32_e64 v79, v211, v79, s[34:35]
	v_cndmask_b32_e32 v80, v211, v80, vcc
	v_cndmask_b32_e64 v81, v211, v81, s[24:25]
	v_cndmask_b32_e64 v82, v211, v82, s[26:27]
	v_cndmask_b32_e64 v83, v211, v83, s[28:29]
	s_nop 0
	s_nop 1
.LBB0_88:
	s_nop 10
	v_max3_f32 v150, v68, s60, v69
	v_max3_f32 v150, v150, v70, v71
	v_max3_f32 v150, v150, v72, v73
	v_max3_f32 v150, v150, v74, v75
	v_max3_f32 v150, v150, v76, v77
	v_max3_f32 v150, v150, v78, v79
	v_max3_f32 v150, v150, v80, v81
	v_max3_f32 v150, v150, v82, v83
	ds_bpermute_b32 v151, v201, v150
	s_cmpk_lt_i32 s14, 0x41
	s_waitcnt lgkmcnt(0)
	v_max3_f32 v202, v149, v150, v151
	v_sub_f32_e32 v68, v68, v202
	v_exp_f32_e32 v68, v68
	v_sub_f32_e32 v69, v69, v202
	v_exp_f32_e32 v69, v69
	v_sub_f32_e32 v70, v70, v202
	v_exp_f32_e32 v70, v70
	v_sub_f32_e32 v71, v71, v202
	v_exp_f32_e32 v71, v71
	v_sub_f32_e32 v72, v72, v202
	v_add_f32_e32 v150, 0, v68
	v_exp_f32_e32 v72, v72
	v_sub_f32_e32 v73, v73, v202
	v_add_f32_e32 v150, v69, v150
	v_exp_f32_e32 v73, v73
	v_sub_f32_e32 v74, v74, v202
	v_sub_f32_e32 v75, v75, v202
	v_sub_f32_e32 v149, v149, v202
	v_add_f32_e32 v150, v70, v150
	v_exp_f32_e32 v74, v74
	v_exp_f32_e32 v75, v75
	v_exp_f32_e32 v196, v149
	v_add_f32_e32 v150, v71, v150
	v_sub_f32_e32 v76, v76, v202
	v_add_f32_e32 v150, v72, v150
	v_exp_f32_e32 v76, v76
	v_sub_f32_e32 v77, v77, v202
	v_add_f32_e32 v150, v73, v150
	v_exp_f32_e32 v77, v77
	v_sub_f32_e32 v78, v78, v202
	v_add_f32_e32 v150, v74, v150
	v_exp_f32_e32 v78, v78
	v_sub_f32_e32 v79, v79, v202
	v_pk_mul_f32 v[18:19], v[18:19], v[196:197] op_sel_hi:[1,0]
	v_pk_mul_f32 v[16:17], v[16:17], v[196:197] op_sel_hi:[1,0]
	v_pk_mul_f32 v[14:15], v[14:15], v[196:197] op_sel_hi:[1,0]
	v_pk_mul_f32 v[12:13], v[12:13], v[196:197] op_sel_hi:[1,0]
	v_pk_mul_f32 v[10:11], v[10:11], v[196:197] op_sel_hi:[1,0]
	v_pk_mul_f32 v[8:9], v[8:9], v[196:197] op_sel_hi:[1,0]
	v_pk_mul_f32 v[6:7], v[6:7], v[196:197] op_sel_hi:[1,0]
	v_pk_mul_f32 v[4:5], v[4:5], v[196:197] op_sel_hi:[1,0]
	v_pk_mul_f32 v[34:35], v[34:35], v[196:197] op_sel_hi:[1,0]
	v_pk_mul_f32 v[32:33], v[32:33], v[196:197] op_sel_hi:[1,0]
	v_pk_mul_f32 v[30:31], v[30:31], v[196:197] op_sel_hi:[1,0]
	v_pk_mul_f32 v[28:29], v[28:29], v[196:197] op_sel_hi:[1,0]
	v_pk_mul_f32 v[26:27], v[26:27], v[196:197] op_sel_hi:[1,0]
	v_pk_mul_f32 v[24:25], v[24:25], v[196:197] op_sel_hi:[1,0]
	v_pk_mul_f32 v[22:23], v[22:23], v[196:197] op_sel_hi:[1,0]
	v_pk_mul_f32 v[20:21], v[20:21], v[196:197] op_sel_hi:[1,0]
	v_cvt_pk_bf16_f32 v68, v68, v69
	v_cvt_pk_bf16_f32 v69, v70, v71
	v_cvt_pk_bf16_f32 v70, v72, v73
	v_cvt_pk_bf16_f32 v71, v74, v75
	v_add_f32_e32 v150, v75, v150
	v_exp_f32_e32 v79, v79
	v_sub_f32_e32 v80, v80, v202
	v_mfma_f32_32x32x16_bf16 v[4:19], v[144:147], v[68:71], v[4:19]
	v_add_f32_e32 v150, v76, v150
	v_exp_f32_e32 v80, v80
	v_sub_f32_e32 v81, v81, v202
	v_add_f32_e32 v150, v77, v150
	v_exp_f32_e32 v81, v81
	v_sub_f32_e32 v82, v82, v202
	v_sub_f32_e32 v83, v83, v202
	v_mfma_f32_32x32x16_bf16 v[20:35], v[140:143], v[68:71], v[20:35]
	v_add_f32_e32 v150, v78, v150
	v_exp_f32_e32 v82, v82
	v_exp_f32_e32 v83, v83
	v_add_f32_e32 v150, v79, v150
	v_add_f32_e32 v150, v80, v150
	v_add_f32_e32 v150, v81, v150
	v_add_f32_e32 v150, v82, v150
	v_cvt_pk_bf16_f32 v68, v76, v77
	v_cvt_pk_bf16_f32 v69, v78, v79
	v_cvt_pk_bf16_f32 v70, v80, v81
	v_cvt_pk_bf16_f32 v71, v82, v83
	v_add_f32_e32 v243, v83, v150
	ds_bpermute_b32 v244, v201, v243
	v_mfma_f32_32x32x16_bf16 v[4:19], v[136:139], v[68:71], v[4:19]
	v_mfma_f32_32x32x16_bf16 v[20:35], v[132:135], v[68:71], v[20:35]
	v_mfma_f32_32x32x16_bf16 v[68:83], v[96:99], v[112:115], 0
	v_mfma_f32_32x32x16_bf16 v[68:83], v[92:95], v[108:111], v[68:83]
	v_mfma_f32_32x32x16_bf16 v[68:83], v[88:91], v[104:107], v[68:83]
	v_mfma_f32_32x32x16_bf16 v[68:83], v[84:87], v[100:103], v[68:83]
	s_cbranch_scc1 .LBB0_90
	v_sub_u32_e32 v84, v237, v218
	v_mov_b32_e32 v85, v219
	s_nop 0
	s_nop 1
	v_cmp_ge_i32_e32 vcc, 0, v84
	v_cmp_ge_i32_e64 s[24:25], 1, v84
	v_cmp_ge_i32_e64 s[26:27], 2, v84
	v_cmp_ge_i32_e64 s[28:29], 3, v84
	v_cmp_ge_i32_e64 s[30:31], 8, v84
	v_cmp_ge_i32_e64 s[34:35], 9, v84
	v_cndmask_b32_e32 v68, v211, v68, vcc
	v_cmp_ge_i32_e32 vcc, 10, v84
	v_cndmask_b32_e64 v69, v211, v69, s[24:25]
	v_cmp_ge_i32_e64 s[24:25], 11, v84
	v_cndmask_b32_e64 v70, v211, v70, s[26:27]
	v_cmp_ge_i32_e64 s[26:27], 16, v84
	v_cndmask_b32_e64 v71, v211, v71, s[28:29]
	v_cmp_ge_i32_e64 s[28:29], 17, v84
	v_cndmask_b32_e64 v72, v211, v72, s[30:31]
	v_cmp_ge_i32_e64 s[30:31], 18, v84
	v_cndmask_b32_e64 v73, v211, v73, s[34:35]
	v_cmp_ge_i32_e64 s[34:35], 19, v84
	v_cndmask_b32_e32 v74, v211, v74, vcc
	v_cmp_ge_i32_e32 vcc, 24, v84
	v_cndmask_b32_e64 v75, v211, v75, s[24:25]
	v_cmp_ge_i32_e64 s[24:25], 25, v84
	v_cndmask_b32_e64 v76, v211, v76, s[26:27]
	v_cmp_ge_i32_e64 s[26:27], 26, v84
	v_cndmask_b32_e64 v77, v211, v77, s[28:29]
	v_cmp_ge_i32_e64 s[28:29], 27, v84
	v_cndmask_b32_e64 v78, v211, v78, s[30:31]
	v_cndmask_b32_e64 v79, v211, v79, s[34:35]
	v_cndmask_b32_e32 v80, v211, v80, vcc
	v_cndmask_b32_e64 v81, v211, v81, s[24:25]
	v_cndmask_b32_e64 v82, v211, v82, s[26:27]
	v_cndmask_b32_e64 v83, v211, v83, s[28:29]
	s_nop 0
	s_nop 1
; #define LAS __attribute__((address_space(3)))
; __device__ __forceinline__ void att_block(const bf16x8 (&kf)[4], const bf16x8 (&qf)[4], const bf16x8 (&va)[4], f32x16& o0, f32x16& o1, float& mrun, float& lrun, bool domask, int lo_, int hi_) {
;     ...
;     const float mnew = fmaxf(mrun, bmax);
;     float lsum = 0.f;
; #pragma unroll
;     for (int i = 0; i < 16; ++i) { st[i] = __builtin_amdgcn_exp2f(st[i] - mnew); lsum += st[i]; }
;     lsum += __shfl_xor(lsum, 32);
;     const float alpha = __builtin_amdgcn_exp2f(mrun - mnew);
;     lrun = lrun * alpha + lsum; mrun = mnew;
; #pragma unroll
;     for (int i = 0; i < 16; ++i) { o0[i] *= alpha; o1[i] *= alpha; }
; #pragma unroll
;     for (int s = 0; s < 2; ++s) { v4u w; w.x = pk2(st[8 * s], st[8 * s + 1]); w.y = pk2(st[8 * s + 2], st[8 * s + 3]); w.z = pk2(st[8 * s + 4], st[8 * s + 5]); w.w = pk2(st[8 * s + 6], st[8 * s + 7]);
;         const bf16x8 pb = __builtin_bit_cast(bf16x8, w);
;         o0 = __builtin_amdgcn_mfma_f32_32x32x16_bf16(va[2 * s], pb, o0, 0, 0, 0);
;         o1 = __builtin_amdgcn_mfma_f32_32x32x16_bf16(va[2 * s + 1], pb, o1, 0, 0, 0); }
; __device__ __forceinline__ void att_phase(unsigned char* ws, LAS unsigned char* lds, int lane, int wave, int G) {
;     ...
;         for (int kb = 0; kb < 6; ++kb) {
;             asm volatile("s_waitcnt vmcnt(0)" ::: "memory");
;             if (kb < 5) ATT_DMA_KV(P, kb + 1, sb ^ 1);
;             else if (hn) ATT_DMA_KV(N, 0, sb ^ 1);
;             bf16x8 kf[4], va[4];
; #pragma unroll
;             for (int kk = 0; kk < 4; ++kk) kf[kk] = *(LAS const bf16x8*)(kfb + sb * 4096 + (((2 * kk + h) ^ (qc & 7)) << 4));
;             LAS const unsigned char* trs = trb + 8192 + sb * 4096;
; #pragma unroll
;             for (int s = 0; s < 2; ++s) {
;                 const s16x4 lo0 = vtr(trs + (16 * s) * VP), hi0 = vtr(trs + (16 * s + 8) * VP);
;                 const s16x4 lo1 = vtr(trs + (16 * s) * VP + 64), hi1 = vtr(trs + (16 * s + 8) * VP + 64);
;                 va[2 * s] = (bf16x8){lo0[0], lo0[1], lo0[2], lo0[3], hi0[0], hi0[1], hi0[2], hi0[3]};
;                 va[2 * s + 1] = (bf16x8){lo1[0], lo1[1], lo1[2], lo1[3], hi1[0], hi1[1], hi1[2], hi1[3]};
;             }
;             if (kb <= 4) {
;                 att_block(kf, qfA, va, oA0, oA1, mA, lA, kb == 0 || kb == 4 || kminA > 32 * kb, mloA - 4 * h - 32 * kb, qc + 128 - 4 * h - 32 * kb);
.LBB0_90:
	v_mul_lo_u32 v84, s52, v189
	s_mov_b32 s58, 0xff800000
	v_add_u32_e32 v198, s53, v84
	s_nop 7
	v_max3_f32 v84, v68, s58, v69
	v_max3_f32 v84, v84, v70, v71
	v_max3_f32 v84, v84, v72, v73
	v_max3_f32 v84, v84, v74, v75
	v_max3_f32 v84, v84, v76, v77
	v_max3_f32 v84, v84, v78, v79
	v_max3_f32 v84, v84, v80, v81
	v_max3_f32 v84, v84, v82, v83
	ds_bpermute_b32 v85, v201, v84
	s_waitcnt lgkmcnt(0)
	s_waitcnt lgkmcnt(0)
	v_max3_f32 v245, v148, v84, v85
	v_sub_f32_e32 v68, v68, v245
	v_exp_f32_e32 v149, v68
	v_sub_f32_e32 v69, v69, v245
	v_exp_f32_e32 v150, v69
	v_sub_f32_e32 v69, v70, v245
	v_exp_f32_e32 v151, v69
	v_sub_f32_e32 v69, v71, v245
	v_exp_f32_e32 v152, v69
	v_sub_f32_e32 v69, v72, v245
	v_add_f32_e32 v68, 0, v149
	v_exp_f32_e32 v153, v69
	v_sub_f32_e32 v69, v73, v245
	v_add_f32_e32 v68, v150, v68
	v_exp_f32_e32 v154, v69
	v_sub_f32_e32 v69, v74, v245
	v_add_f32_e32 v68, v151, v68
	v_exp_f32_e32 v155, v69
	v_sub_f32_e32 v69, v75, v245
	v_add_f32_e32 v68, v152, v68
	v_exp_f32_e32 v156, v69
	v_sub_f32_e32 v69, v76, v245
	v_add_f32_e32 v68, v153, v68
	v_exp_f32_e32 v157, v69
	v_sub_f32_e32 v69, v77, v245
	v_add_f32_e32 v68, v154, v68
	v_exp_f32_e32 v158, v69
	v_sub_f32_e32 v69, v78, v245
	v_add_f32_e32 v68, v155, v68
	v_exp_f32_e32 v159, v69
	v_sub_f32_e32 v69, v79, v245
	v_add_f32_e32 v68, v156, v68
	v_exp_f32_e32 v160, v69
	v_sub_f32_e32 v69, v80, v245
	v_add_f32_e32 v68, v157, v68
	v_exp_f32_e32 v161, v69
	v_sub_f32_e32 v69, v81, v245
	v_add_f32_e32 v68, v158, v68
	v_exp_f32_e32 v162, v69
	v_sub_f32_e32 v69, v82, v245
	v_add_f32_e32 v68, v159, v68
	v_exp_f32_e32 v163, v69
	v_sub_f32_e32 v69, v83, v245
	v_add_f32_e32 v68, v160, v68
	v_exp_f32_e32 v164, v69
	v_add_f32_e32 v68, v161, v68
	v_add_f32_e32 v68, v162, v68
	v_add_f32_e32 v68, v163, v68
	v_add_f32_e32 v241, v164, v68
	v_sub_f32_e32 v68, v148, v245
	v_exp_f32_e32 v194, v68
	ds_bpermute_b32 v242, v201, v241
	v_pk_mul_f32 v[82:83], v[50:51], v[194:195] op_sel_hi:[1,0]
	v_pk_mul_f32 v[80:81], v[48:49], v[194:195] op_sel_hi:[1,0]
	v_pk_mul_f32 v[78:79], v[46:47], v[194:195] op_sel_hi:[1,0]
	v_pk_mul_f32 v[76:77], v[44:45], v[194:195] op_sel_hi:[1,0]
	v_pk_mul_f32 v[74:75], v[42:43], v[194:195] op_sel_hi:[1,0]
	v_pk_mul_f32 v[72:73], v[40:41], v[194:195] op_sel_hi:[1,0]
	v_pk_mul_f32 v[70:71], v[38:39], v[194:195] op_sel_hi:[1,0]
	v_pk_mul_f32 v[68:69], v[36:37], v[194:195] op_sel_hi:[1,0]
	v_pk_mul_f32 v[98:99], v[66:67], v[194:195] op_sel_hi:[1,0]
	v_pk_mul_f32 v[96:97], v[64:65], v[194:195] op_sel_hi:[1,0]
	v_pk_mul_f32 v[94:95], v[62:63], v[194:195] op_sel_hi:[1,0]
	v_pk_mul_f32 v[92:93], v[60:61], v[194:195] op_sel_hi:[1,0]
	v_pk_mul_f32 v[90:91], v[58:59], v[194:195] op_sel_hi:[1,0]
	v_pk_mul_f32 v[88:89], v[56:57], v[194:195] op_sel_hi:[1,0]
	v_pk_mul_f32 v[86:87], v[54:55], v[194:195] op_sel_hi:[1,0]
	v_pk_mul_f32 v[84:85], v[52:53], v[194:195] op_sel_hi:[1,0]
	v_cvt_pk_bf16_f32 v36, v149, v150
	v_cvt_pk_bf16_f32 v37, v151, v152
	v_cvt_pk_bf16_f32 v38, v153, v154
	v_cvt_pk_bf16_f32 v39, v155, v156
	s_nop 1
	v_mfma_f32_32x32x16_bf16 v[68:83], v[144:147], v[36:39], v[68:83]
	v_mfma_f32_32x32x16_bf16 v[84:99], v[140:143], v[36:39], v[84:99]
	v_cvt_pk_bf16_f32 v36, v157, v158
	v_cvt_pk_bf16_f32 v37, v159, v160
	v_cvt_pk_bf16_f32 v38, v161, v162
	v_cvt_pk_bf16_f32 v39, v163, v164
	s_nop 1
	v_mfma_f32_32x32x16_bf16 v[68:83], v[136:139], v[36:39], v[68:83]
	v_mfma_f32_32x32x16_bf16 v[84:99], v[132:135], v[36:39], v[84:99]
	v_mul_lo_u32 v36, s56, v222
	v_add_u32_e32 v40, s11, v36
	v_max_i32_e32 v164, 0, v40
	v_lshl_add_u64 v[36:37], s[12:13], 0, v[164:165]
	v_lshlrev_b64 v[36:37], 7, v[36:37]
	s_waitcnt vmcnt(0)
	v_lshl_add_u64 v[38:39], v[180:181], 0, v[36:37]
	s_mov_b32 m0, s57
	v_add_u32_e32 v40, s6, v40
	global_load_lds_dwordx4 v[38:39], off
	v_lshl_add_u64 v[36:37], v[182:183], 0, v[36:37]
	s_mov_b32 m0, s7
	v_max_i32_e32 v164, 0, v40
	global_load_lds_dwordx4 v[36:37], off
	v_lshl_add_u64 v[36:37], s[12:13], 0, v[164:165]
	v_lshlrev_b64 v[36:37], 7, v[36:37]
	v_readlane_b32 s7, v254, 28
	v_lshl_add_u64 v[38:39], v[180:181], 0, v[36:37]
	s_mov_b32 m0, s7
	v_readlane_b32 s7, v254, 29
	v_add_u32_e32 v40, s6, v40
	global_load_lds_dwordx4 v[38:39], off
	v_lshl_add_u64 v[36:37], v[182:183], 0, v[36:37]
	s_mov_b32 m0, s7
	v_max_i32_e32 v164, 0, v40
	global_load_lds_dwordx4 v[36:37], off
	v_lshl_add_u64 v[36:37], s[12:13], 0, v[164:165]
	v_lshlrev_b64 v[36:37], 7, v[36:37]
	v_lshl_add_u64 v[38:39], v[180:181], 0, v[36:37]
	s_mov_b32 m0, s15
	v_lshl_add_u64 v[36:37], v[182:183], 0, v[36:37]
	global_load_lds_dwordx4 v[38:39], off
	s_mov_b32 m0, s17
	v_sub_u32_e32 v52, v199, v223
	global_load_lds_dwordx4 v[36:37], off
	v_add_u32_e32 v36, s6, v40
	v_max_i32_e32 v164, 0, v36
	v_lshl_add_u64 v[36:37], s[12:13], 0, v[164:165]
	v_lshlrev_b64 v[36:37], 7, v[36:37]
	v_lshl_add_u64 v[38:39], v[180:181], 0, v[36:37]
	s_mov_b32 m0, s21
	v_readlane_b32 s6, v254, 30
	global_load_lds_dwordx4 v[38:39], off
	v_lshl_add_u64 v[36:37], v[182:183], 0, v[36:37]
	s_mov_b32 m0, s6
	v_mov_b32_e32 v53, v224
	global_load_lds_dwordx4 v[36:37], off
	ds_read_b128 v[160:163], v225
	ds_read_b128 v[156:159], v226
	ds_read_b128 v[152:155], v227
	ds_read_b128 v[148:151], v228
	s_waitcnt vmcnt(0)
	ds_read_b64_tr_b16 v[144:145], v229 offset:8192
	ds_read_b64_tr_b16 v[146:147], v229 offset:9216
	ds_read_b64_tr_b16 v[140:141], v229 offset:8256
	ds_read_b64_tr_b16 v[142:143], v229 offset:9280
	ds_read_b64_tr_b16 v[136:137], v229 offset:10240
	ds_read_b64_tr_b16 v[138:139], v229 offset:11264
	ds_read_b64_tr_b16 v[132:133], v229 offset:10304
	ds_read_b64_tr_b16 v[134:135], v229 offset:11328
	s_waitcnt lgkmcnt(0)
; __device__ __forceinline__ unsigned pk2(float lo, float hi) { return pg8::cvt_pk_bf16(lo, hi); }
; __device__ __forceinline__ void att_block(const bf16x8 (&kf)[4], const bf16x8 (&qf)[4], const bf16x8 (&va)[4], f32x16& o0, f32x16& o1, float& mrun, float& lrun, bool domask, int lo_, int hi_) {
;     ...
;     if (domask) {
;         asm volatile("" : "+v"(lo_), "+v"(hi_));
; #pragma unroll
;         for (int i = 0; i < 16; ++i) { const int ci = (i & 3) + 8 * (i >> 2); st[i] = ((ci - lo_) | (hi_ - ci)) < 0 ? -INFINITY : st[i]; }
;     }
;     float bmax = -INFINITY;
; #pragma unroll
;     for (int i = 0; i < 16; ++i) bmax = fmaxf(bmax, st[i]);
;     bmax = fmaxf(bmax, __shfl_xor(bmax, 32));
;     const float mnew = fmaxf(mrun, bmax);
;     float lsum = 0.f;
; #pragma unroll
;     for (int i = 0; i < 16; ++i) { st[i] = __builtin_amdgcn_exp2f(st[i] - mnew); lsum += st[i]; }
;     lsum += __shfl_xor(lsum, 32);
;     const float alpha = __builtin_amdgcn_exp2f(mrun - mnew);
;     lrun = lrun * alpha + lsum; mrun = mnew;
; #pragma unroll
;     for (int i = 0; i < 16; ++i) { o0[i] *= alpha; o1[i] *= alpha; }
; #pragma unroll
;     for (int s = 0; s < 2; ++s) { v4u w; w.x = pk2(st[8 * s], st[8 * s + 1]); w.y = pk2(st[8 * s + 2], st[8 * s + 3]); w.z = pk2(st[8 * s + 4], st[8 * s + 5]); w.w = pk2(st[8 * s + 6], st[8 * s + 7]);
;         const bf16x8 pb = __builtin_bit_cast(bf16x8, w);
;         o0 = __builtin_amdgcn_mfma_f32_32x32x16_bf16(va[2 * s], pb, o0, 0, 0, 0);
;         o1 = __builtin_amdgcn_mfma_f32_32x32x16_bf16(va[2 * s + 1], pb, o1, 0, 0, 0); }
; __device__ __forceinline__ void att_phase(unsigned char* ws, LAS unsigned char* lds, int lane, int wave, int G) {
;     ...
;             if (kb <= 4) {
;                 att_block(kf, qfA, va, oA0, oA1, mA, lA, kb == 0 || kb == 4 || kminA > 32 * kb, mloA - 4 * h - 32 * kb, qc + 128 - 4 * h - 32 * kb);
;                 if (kb == 4 && hn) ATT_LOAD_Q(qfA, N, 0);
;             }
;             if (kb >= 1) {
;                 att_block(kf, qfB, va, oB0, oB1, mB, lB, kb == 1 || kb == 5 || kminB > 32 * (kb - 1), mloB - 4 * h - 32 * (kb - 1), qc + 128 - 4 * h - 32 * (kb - 1));
;                 if (kb == 5 && hn) ATT_LOAD_Q(qfB, N, 1);
;             }
	v_mfma_f32_32x32x16_bf16 v[36:51], v[160:163], v[128:131], 0
	s_nop 0
	v_mfma_f32_32x32x16_bf16 v[36:51], v[156:159], v[124:127], v[36:51]
	v_mfma_f32_32x32x16_bf16 v[36:51], v[152:155], v[120:123], v[36:51]
	v_mfma_f32_32x32x16_bf16 v[36:51], v[148:151], v[116:119], v[36:51]
	s_nop 11
	v_cmp_le_i32_e32 vcc, 0, v53
	v_cmp_le_i32_e64 s[24:25], 1, v53
	v_cmp_le_i32_e64 s[26:27], 2, v53
	v_cmp_le_i32_e64 s[28:29], 3, v53
	v_cmp_le_i32_e64 s[30:31], 8, v53
	v_cmp_le_i32_e64 s[34:35], 9, v53
	v_cndmask_b32_e32 v36, v211, v36, vcc
	v_cmp_le_i32_e32 vcc, 10, v53
	v_cndmask_b32_e64 v37, v211, v37, s[24:25]
	v_cmp_le_i32_e64 s[24:25], 11, v53
	v_cndmask_b32_e64 v38, v211, v38, s[26:27]
	v_cmp_le_i32_e64 s[26:27], 16, v53
	v_cndmask_b32_e64 v39, v211, v39, s[28:29]
	v_cmp_le_i32_e64 s[28:29], 17, v53
	v_cndmask_b32_e64 v40, v211, v40, s[30:31]
	v_cmp_le_i32_e64 s[30:31], 18, v53
	v_cndmask_b32_e64 v41, v211, v41, s[34:35]
	v_cmp_le_i32_e64 s[34:35], 19, v53
	v_cndmask_b32_e32 v42, v211, v42, vcc
	v_cmp_le_i32_e32 vcc, 24, v53
	v_cndmask_b32_e64 v43, v211, v43, s[24:25]
	v_cmp_le_i32_e64 s[24:25], 25, v53
	v_cndmask_b32_e64 v44, v211, v44, s[26:27]
	v_cmp_le_i32_e64 s[26:27], 26, v53
	v_cndmask_b32_e64 v45, v211, v45, s[28:29]
	v_cmp_le_i32_e64 s[28:29], 27, v53
	v_cndmask_b32_e64 v46, v211, v46, s[30:31]
	v_cndmask_b32_e64 v47, v211, v47, s[34:35]
	v_cndmask_b32_e32 v48, v211, v48, vcc
	v_cndmask_b32_e64 v49, v211, v49, s[24:25]
	v_cndmask_b32_e64 v50, v211, v50, s[26:27]
	v_cndmask_b32_e64 v51, v211, v51, s[28:29]
	s_nop 0
	v_max3_f32 v52, v36, s58, v37
	v_max3_f32 v52, v52, v38, v39
	v_max3_f32 v52, v52, v40, v41
	v_max3_f32 v52, v52, v42, v43
	v_max3_f32 v52, v52, v44, v45
	v_max3_f32 v52, v52, v46, v47
	v_max3_f32 v52, v52, v48, v49
	v_max3_f32 v52, v52, v50, v51
	ds_bpermute_b32 v53, v201, v52
	s_andn2_b64 vcc, exec, s[2:3]
	s_waitcnt lgkmcnt(0)
	v_max3_f32 v200, v202, v52, v53
	v_sub_f32_e32 v36, v36, v200
	v_exp_f32_e32 v164, v36
	v_sub_f32_e32 v37, v37, v200
	v_exp_f32_e32 v166, v37
	v_sub_f32_e32 v37, v38, v200
	v_exp_f32_e32 v167, v37
	v_sub_f32_e32 v37, v39, v200
	v_exp_f32_e32 v199, v37
	v_sub_f32_e32 v37, v40, v200
	v_add_f32_e32 v36, 0, v164
	v_exp_f32_e32 v248, v37
	v_sub_f32_e32 v37, v41, v200
	v_add_f32_e32 v36, v166, v36
	v_exp_f32_e32 v249, v37
	v_sub_f32_e32 v37, v42, v200
	v_add_f32_e32 v36, v167, v36
	v_exp_f32_e32 v250, v37
	v_sub_f32_e32 v37, v43, v200
	v_add_f32_e32 v36, v199, v36
	v_exp_f32_e32 v251, v37
	v_sub_f32_e32 v37, v44, v200
	v_add_f32_e32 v36, v248, v36
	v_exp_f32_e32 v252, v37
	v_sub_f32_e32 v37, v45, v200
	v_add_f32_e32 v36, v249, v36
	v_exp_f32_e32 v203, v37
	v_sub_f32_e32 v37, v46, v200
	v_add_f32_e32 v36, v250, v36
	v_exp_f32_e32 v168, v37
	v_sub_f32_e32 v37, v47, v200
	v_add_f32_e32 v36, v251, v36
	v_exp_f32_e32 v169, v37
	v_sub_f32_e32 v37, v48, v200
	v_add_f32_e32 v36, v252, v36
	v_exp_f32_e32 v212, v37
	v_sub_f32_e32 v37, v49, v200
	v_add_f32_e32 v36, v203, v36
	v_exp_f32_e32 v209, v37
	v_sub_f32_e32 v37, v50, v200
	v_add_f32_e32 v36, v168, v36
	v_exp_f32_e32 v197, v37
	v_sub_f32_e32 v37, v51, v200
	v_add_f32_e32 v36, v169, v36
	v_exp_f32_e32 v195, v37
	v_add_f32_e32 v36, v212, v36
	v_add_f32_e32 v36, v209, v36
	v_add_f32_e32 v36, v197, v36
	v_add_f32_e32 v246, v195, v36
	v_sub_f32_e32 v36, v202, v200
	v_exp_f32_e32 v202, v36
	ds_bpermute_b32 v247, v201, v246
	v_pk_mul_f32 v[66:67], v[18:19], v[202:203] op_sel_hi:[1,0]
	v_pk_mul_f32 v[64:65], v[16:17], v[202:203] op_sel_hi:[1,0]
	v_pk_mul_f32 v[62:63], v[14:15], v[202:203] op_sel_hi:[1,0]
	v_pk_mul_f32 v[60:61], v[12:13], v[202:203] op_sel_hi:[1,0]
	v_pk_mul_f32 v[58:59], v[10:11], v[202:203] op_sel_hi:[1,0]
	v_pk_mul_f32 v[56:57], v[8:9], v[202:203] op_sel_hi:[1,0]
	v_pk_mul_f32 v[54:55], v[6:7], v[202:203] op_sel_hi:[1,0]
	v_pk_mul_f32 v[52:53], v[4:5], v[202:203] op_sel_hi:[1,0]
	v_pk_mul_f32 v[50:51], v[34:35], v[202:203] op_sel_hi:[1,0]
	v_pk_mul_f32 v[48:49], v[32:33], v[202:203] op_sel_hi:[1,0]
	v_pk_mul_f32 v[46:47], v[30:31], v[202:203] op_sel_hi:[1,0]
	v_pk_mul_f32 v[44:45], v[28:29], v[202:203] op_sel_hi:[1,0]
	v_pk_mul_f32 v[42:43], v[26:27], v[202:203] op_sel_hi:[1,0]
	v_pk_mul_f32 v[40:41], v[24:25], v[202:203] op_sel_hi:[1,0]
	v_pk_mul_f32 v[38:39], v[22:23], v[202:203] op_sel_hi:[1,0]
	v_pk_mul_f32 v[36:37], v[20:21], v[202:203] op_sel_hi:[1,0]
	v_cvt_pk_bf16_f32 v4, v164, v166
	v_cvt_pk_bf16_f32 v5, v167, v199
	v_cvt_pk_bf16_f32 v6, v248, v249
	v_cvt_pk_bf16_f32 v7, v250, v251
	s_nop 1
	v_mfma_f32_32x32x16_bf16 v[52:67], v[144:147], v[4:7], v[52:67]
	v_mfma_f32_32x32x16_bf16 v[36:51], v[140:143], v[4:7], v[36:51]
	v_cvt_pk_bf16_f32 v4, v252, v203
	v_cvt_pk_bf16_f32 v5, v168, v169
	v_cvt_pk_bf16_f32 v6, v212, v209
	v_cvt_pk_bf16_f32 v7, v197, v195
	s_nop 1
	v_mfma_f32_32x32x16_bf16 v[52:67], v[136:139], v[4:7], v[52:67]
	v_mfma_f32_32x32x16_bf16 v[36:51], v[132:135], v[4:7], v[36:51]
	v_cndmask_b32_e64 v4, 0, 1, s[2:3]
	v_cmp_ne_u32_e64 s[6:7], 1, v4
	s_cbranch_vccnz .LBB0_92
	v_ashrrev_i32_e32 v199, 31, v198
	v_lshl_add_u64 v[4:5], s[0:1], 0, v[198:199]
	v_lshlrev_b64 v[4:5], 7, v[4:5]
	v_lshl_add_u64 v[4:5], v[186:187], 0, v[4:5]
	global_load_dwordx4 v[128:131], v[4:5], off
	global_load_dwordx4 v[124:127], v[4:5], off offset:32
	global_load_dwordx4 v[120:123], v[4:5], off offset:64
	global_load_dwordx4 v[116:119], v[4:5], off offset:96
.LBB0_92:
	v_mfma_f32_32x32x16_bf16 v[4:19], v[160:163], v[112:115], 0
	s_cmpk_lt_i32 s14, 0x61
	v_mfma_f32_32x32x16_bf16 v[4:19], v[156:159], v[108:111], v[4:19]
	v_mfma_f32_32x32x16_bf16 v[4:19], v[152:155], v[104:107], v[4:19]
	v_mfma_f32_32x32x16_bf16 v[4:19], v[148:151], v[100:103], v[4:19]
	s_cbranch_scc1 .LBB0_94
	v_sub_u32_e32 v20, v237, v220
	v_mov_b32_e32 v21, v221
	s_nop 0
	s_nop 1
	v_cmp_ge_i32_e32 vcc, 0, v20
	v_cmp_ge_i32_e64 s[24:25], 1, v20
	v_cmp_ge_i32_e64 s[26:27], 2, v20
	v_cmp_ge_i32_e64 s[28:29], 3, v20
	v_cmp_ge_i32_e64 s[30:31], 8, v20
	v_cmp_ge_i32_e64 s[34:35], 9, v20
	v_cndmask_b32_e32 v4, v211, v4, vcc
	v_cmp_ge_i32_e32 vcc, 10, v20
	v_cndmask_b32_e64 v5, v211, v5, s[24:25]
	v_cmp_ge_i32_e64 s[24:25], 11, v20
	v_cndmask_b32_e64 v6, v211, v6, s[26:27]
	v_cmp_ge_i32_e64 s[26:27], 16, v20
	v_cndmask_b32_e64 v7, v211, v7, s[28:29]
	v_cmp_ge_i32_e64 s[28:29], 17, v20
	v_cndmask_b32_e64 v8, v211, v8, s[30:31]
	v_cmp_ge_i32_e64 s[30:31], 18, v20
	v_cndmask_b32_e64 v9, v211, v9, s[34:35]
	v_cmp_ge_i32_e64 s[34:35], 19, v20
	v_cndmask_b32_e32 v10, v211, v10, vcc
	v_cmp_ge_i32_e32 vcc, 24, v20
	v_cndmask_b32_e64 v11, v211, v11, s[24:25]
	v_cmp_ge_i32_e64 s[24:25], 25, v20
	v_cndmask_b32_e64 v12, v211, v12, s[26:27]
	v_cmp_ge_i32_e64 s[26:27], 26, v20
	v_cndmask_b32_e64 v13, v211, v13, s[28:29]
	v_cmp_ge_i32_e64 s[28:29], 27, v20
	v_cndmask_b32_e64 v14, v211, v14, s[30:31]
	v_cndmask_b32_e64 v15, v211, v15, s[34:35]
	v_cndmask_b32_e32 v16, v211, v16, vcc
	v_cndmask_b32_e64 v17, v211, v17, s[24:25]
	v_cndmask_b32_e64 v18, v211, v18, s[26:27]
	v_cndmask_b32_e64 v19, v211, v19, s[28:29]
	s_nop 0
	s_nop 1

; __device__ __forceinline__ unsigned pk2(float lo, float hi) { return pg8::cvt_pk_bf16(lo, hi); }
; __device__ __forceinline__ void att_block(const bf16x8 (&kf)[4], const bf16x8 (&qf)[4], const bf16x8 (&va)[4], f32x16& o0, f32x16& o1, float& mrun, float& lrun, bool domask, int lo_, int hi_) {
;     ...
;     if (domask) {
;         asm volatile("" : "+v"(lo_), "+v"(hi_));
; #pragma unroll
;         for (int i = 0; i < 16; ++i) { const int ci = (i & 3) + 8 * (i >> 2); st[i] = ((ci - lo_) | (hi_ - ci)) < 0 ? -INFINITY : st[i]; }
;     }
;     float bmax = -INFINITY;
; #pragma unroll
;     for (int i = 0; i < 16; ++i) bmax = fmaxf(bmax, st[i]);
;     bmax = fmaxf(bmax, __shfl_xor(bmax, 32));
;     const float mnew = fmaxf(mrun, bmax);
;     float lsum = 0.f;
; #pragma unroll
;     for (int i = 0; i < 16; ++i) { st[i] = __builtin_amdgcn_exp2f(st[i] - mnew); lsum += st[i]; }
;     lsum += __shfl_xor(lsum, 32);
;     const float alpha = __builtin_amdgcn_exp2f(mrun - mnew);
;     lrun = lrun * alpha + lsum; mrun = mnew;
; #pragma unroll
;     for (int i = 0; i < 16; ++i) { o0[i] *= alpha; o1[i] *= alpha; }
; #pragma unroll
;     for (int s = 0; s < 2; ++s) { v4u w; w.x = pk2(st[8 * s], st[8 * s + 1]); w.y = pk2(st[8 * s + 2], st[8 * s + 3]); w.z = pk2(st[8 * s + 4], st[8 * s + 5]); w.w = pk2(st[8 * s + 6], st[8 * s + 7]);
;         const bf16x8 pb = __builtin_bit_cast(bf16x8, w);
;         o0 = __builtin_amdgcn_mfma_f32_32x32x16_bf16(va[2 * s], pb, o0, 0, 0, 0);
;         o1 = __builtin_amdgcn_mfma_f32_32x32x16_bf16(va[2 * s + 1], pb, o1, 0, 0, 0); }
; __device__ __forceinline__ void att_phase(unsigned char* ws, LAS unsigned char* lds, int lane, int wave, int G) {
;     ...
;             if (kb <= 4) {
;                 att_block(kf, qfA, va, oA0, oA1, mA, lA, kb == 0 || kb == 4 || kminA > 32 * kb, mloA - 4 * h - 32 * kb, qc + 128 - 4 * h - 32 * kb);
;                 if (kb == 4 && hn) ATT_LOAD_Q(qfA, N, 0);
;             }
;             if (kb >= 1) {
;                 att_block(kf, qfB, va, oB0, oB1, mB, lB, kb == 1 || kb == 5 || kminB > 32 * (kb - 1), mloB - 4 * h - 32 * (kb - 1), qc + 128 - 4 * h - 32 * (kb - 1));
;                 if (kb == 5 && hn) ATT_LOAD_Q(qfB, N, 1);
;             }
.LBB0_96:
	ds_read_b128 v[68:71], v225 offset:4096
	ds_read_b128 v[132:135], v226 offset:4096
	ds_read_b128 v[136:139], v227 offset:4096
	ds_read_b128 v[140:143], v228 offset:4096
	s_waitcnt vmcnt(0)
	ds_read_b64_tr_b16 v[92:93], v229 offset:12288
	ds_read_b64_tr_b16 v[94:95], v229 offset:13312
	ds_read_b64_tr_b16 v[86:87], v229 offset:13376
	ds_read_b64_tr_b16 v[84:85], v229 offset:12352
	s_waitcnt lgkmcnt(0)
	v_mfma_f32_32x32x16_bf16 v[68:83], v[68:71], v[112:115], 0
	v_sub_u32_e32 v144, v237, v223
	v_mov_b32_e32 v145, v224
	ds_read_b64_tr_b16 v[96:97], v229 offset:14336
	ds_read_b64_tr_b16 v[98:99], v229 offset:15360
	ds_read_b64_tr_b16 v[90:91], v229 offset:15424
	ds_read_b64_tr_b16 v[88:89], v229 offset:14400
	s_mov_b32 s14, 0xff800000
	v_mfma_f32_32x32x16_bf16 v[68:83], v[132:135], v[108:111], v[68:83]
	v_mfma_f32_32x32x16_bf16 v[68:83], v[136:139], v[104:107], v[68:83]
	v_mfma_f32_32x32x16_bf16 v[68:83], v[140:143], v[100:103], v[68:83]
	s_nop 11
	v_cmp_le_i32_e32 vcc, 0, v145
	v_cmp_le_i32_e64 s[24:25], 1, v145
	v_cmp_le_i32_e64 s[26:27], 2, v145
	v_cmp_le_i32_e64 s[28:29], 3, v145
	v_cmp_le_i32_e64 s[30:31], 8, v145
	v_cmp_le_i32_e64 s[34:35], 9, v145
	v_cndmask_b32_e32 v68, v211, v68, vcc
	v_cmp_le_i32_e32 vcc, 10, v145
	v_cndmask_b32_e64 v69, v211, v69, s[24:25]
	v_cmp_le_i32_e64 s[24:25], 11, v145
	v_cndmask_b32_e64 v70, v211, v70, s[26:27]
	v_cmp_le_i32_e64 s[26:27], 16, v145
	v_cndmask_b32_e64 v71, v211, v71, s[28:29]
	v_cmp_le_i32_e64 s[28:29], 17, v145
	v_cndmask_b32_e64 v72, v211, v72, s[30:31]
	v_cmp_le_i32_e64 s[30:31], 18, v145
	v_cndmask_b32_e64 v73, v211, v73, s[34:35]
	v_cmp_le_i32_e64 s[34:35], 19, v145
	v_cndmask_b32_e32 v74, v211, v74, vcc
	v_cmp_le_i32_e32 vcc, 24, v145
	v_cndmask_b32_e64 v75, v211, v75, s[24:25]
	v_cmp_le_i32_e64 s[24:25], 25, v145
	v_cndmask_b32_e64 v132, v211, v76, s[26:27]
	v_cmp_le_i32_e64 s[26:27], 26, v145
	v_cndmask_b32_e64 v77, v211, v77, s[28:29]
	v_cmp_le_i32_e64 s[28:29], 27, v145
	v_cndmask_b32_e64 v78, v211, v78, s[30:31]
	v_cndmask_b32_e64 v79, v211, v79, s[34:35]
	v_cndmask_b32_e32 v80, v211, v80, vcc
	v_cndmask_b32_e64 v81, v211, v81, s[24:25]
	v_cndmask_b32_e64 v82, v211, v82, s[26:27]
	v_cndmask_b32_e64 v83, v211, v83, s[28:29]
	s_nop 0
	s_nop 1
	s_nop 1
	s_nop 0
	v_max3_f32 v76, v68, s14, v69
	v_max3_f32 v76, v76, v70, v71
	v_max3_f32 v76, v76, v72, v73
	v_max3_f32 v76, v76, v74, v75
	v_max3_f32 v76, v76, v132, v77
	v_max3_f32 v76, v76, v78, v79
	v_max3_f32 v76, v76, v80, v81
	v_max3_f32 v76, v76, v82, v83
	ds_bpermute_b32 v133, v201, v76
	s_and_b64 vcc, exec, s[6:7]
	s_waitcnt lgkmcnt(0)
	v_max3_f32 v76, v151, v76, v133
	v_sub_f32_e32 v68, v68, v76
	v_exp_f32_e32 v68, v68
	v_sub_f32_e32 v69, v69, v76
	v_exp_f32_e32 v69, v69
	v_sub_f32_e32 v70, v70, v76
	v_exp_f32_e32 v70, v70
	v_sub_f32_e32 v71, v71, v76
	v_exp_f32_e32 v71, v71
	v_sub_f32_e32 v72, v72, v76
	v_add_f32_e32 v133, 0, v68
	v_exp_f32_e32 v72, v72
	v_sub_f32_e32 v73, v73, v76
	v_add_f32_e32 v133, v69, v133
	v_exp_f32_e32 v73, v73
	v_sub_f32_e32 v74, v74, v76
	v_add_f32_e32 v133, v70, v133
	v_exp_f32_e32 v74, v74
	v_sub_f32_e32 v75, v75, v76
	v_add_f32_e32 v133, v71, v133
	v_exp_f32_e32 v75, v75
	v_sub_f32_e32 v132, v132, v76
	v_add_f32_e32 v133, v72, v133
	v_exp_f32_e32 v132, v132
	v_sub_f32_e32 v77, v77, v76
	v_add_f32_e32 v133, v73, v133
	v_exp_f32_e32 v77, v77
	v_sub_f32_e32 v78, v78, v76
	v_add_f32_e32 v133, v74, v133
	v_exp_f32_e32 v134, v78
	v_add_f32_e32 v78, v75, v133
	v_add_f32_e32 v78, v132, v78
	v_add_f32_e32 v78, v77, v78
	v_add_f32_e32 v133, v134, v78
	v_sub_f32_e32 v78, v79, v76
	v_exp_f32_e32 v79, v78
	v_sub_f32_e32 v78, v80, v76
	v_exp_f32_e32 v80, v78
	v_sub_f32_e32 v78, v151, v76
	v_exp_f32_e32 v78, v78
	v_cvt_pk_bf16_f32 v68, v68, v69
	v_cvt_pk_bf16_f32 v69, v70, v71
	v_cvt_pk_bf16_f32 v70, v72, v73
	v_pk_mul_f32 v[34:35], v[34:35], v[78:79] op_sel_hi:[1,0]
	v_pk_mul_f32 v[32:33], v[32:33], v[78:79] op_sel_hi:[1,0]
	v_pk_mul_f32 v[30:31], v[30:31], v[78:79] op_sel_hi:[1,0]
	v_pk_mul_f32 v[28:29], v[28:29], v[78:79] op_sel_hi:[1,0]
	v_pk_mul_f32 v[26:27], v[26:27], v[78:79] op_sel_hi:[1,0]
	v_pk_mul_f32 v[24:25], v[24:25], v[78:79] op_sel_hi:[1,0]
	v_pk_mul_f32 v[22:23], v[22:23], v[78:79] op_sel_hi:[1,0]
	v_pk_mul_f32 v[20:21], v[20:21], v[78:79] op_sel_hi:[1,0]
	v_pk_mul_f32 v[18:19], v[18:19], v[78:79] op_sel_hi:[1,0]
	v_cvt_pk_bf16_f32 v71, v74, v75
	v_pk_mul_f32 v[16:17], v[16:17], v[78:79] op_sel_hi:[1,0]
	v_pk_mul_f32 v[14:15], v[14:15], v[78:79] op_sel_hi:[1,0]
	v_pk_mul_f32 v[12:13], v[12:13], v[78:79] op_sel_hi:[1,0]
	v_pk_mul_f32 v[10:11], v[10:11], v[78:79] op_sel_hi:[1,0]
	v_pk_mul_f32 v[8:9], v[8:9], v[78:79] op_sel_hi:[1,0]
	v_pk_mul_f32 v[6:7], v[6:7], v[78:79] op_sel_hi:[1,0]
	v_pk_mul_f32 v[4:5], v[4:5], v[78:79] op_sel_hi:[1,0]
	v_mfma_f32_32x32x16_bf16 v[20:35], v[92:95], v[68:71], v[20:35]
	v_sub_f32_e32 v81, v81, v76
	v_sub_f32_e32 v82, v82, v76
	v_exp_f32_e32 v81, v81
	v_exp_f32_e32 v72, v82
	v_add_f32_e32 v74, v79, v133
	v_add_f32_e32 v74, v80, v74
	v_add_f32_e32 v74, v81, v74
	v_mfma_f32_32x32x16_bf16 v[4:19], v[84:87], v[68:71], v[4:19]
	v_sub_f32_e32 v68, v83, v76
	v_exp_f32_e32 v73, v68
	v_cvt_pk_bf16_f32 v68, v132, v77
	v_cvt_pk_bf16_f32 v69, v134, v79
	v_cvt_pk_bf16_f32 v70, v80, v81
	v_cvt_pk_bf16_f32 v71, v72, v73
	v_add_f32_e32 v72, v72, v74
	v_add_f32_e32 v77, v73, v72
	v_mfma_f32_32x32x16_bf16 v[20:35], v[96:99], v[68:71], v[20:35]
	ds_bpermute_b32 v79, v201, v77
	v_mfma_f32_32x32x16_bf16 v[4:19], v[88:91], v[68:71], v[4:19]
	s_cbranch_vccnz .LBB0_98
	v_lshl_add_u32 v68, s52, 5, v198
	v_ashrrev_i32_e32 v69, 31, v68
	v_lshl_add_u64 v[68:69], s[0:1], 0, v[68:69]
	v_lshlrev_b64 v[68:69], 7, v[68:69]
	v_lshl_add_u64 v[68:69], v[186:187], 0, v[68:69]
	global_load_dwordx4 v[112:115], v[68:69], off
	global_load_dwordx4 v[108:111], v[68:69], off offset:32
	global_load_dwordx4 v[104:107], v[68:69], off offset:64
	global_load_dwordx4 v[100:103], v[68:69], off offset:96
